# P0 weight transposes: both 16-load iterations of a tile issued before the first LDS write (32 loads in flight per wave, renamed registers)
# baseline (speedup 1.0000x reference)
.LBB0_18:
	s_lshl_b32 s19, s3, 1
	s_lshl_b32 s20, s4, 1
	v_or_b32_e32 v4, s20, v36
	s_add_i32 s22, s19, 4
	s_add_i32 s23, s20, 4
	v_mov_b32_e32 v51, v5
	s_add_i32 s27, s20, 8
	v_lshlrev_b64 v[64:65], 12, v[4:5]
	v_or_b32_e32 v50, s22, v3
	v_or_b32_e32 v4, s23, v36
	v_mov_b32_e32 v49, v5
	v_or_b32_e32 v48, s19, v3
	s_add_i32 s29, s20, 12
	v_lshlrev_b64 v[50:51], 12, v[50:51]
	v_lshlrev_b64 v[66:67], 12, v[4:5]
	v_or_b32_e32 v4, s27, v36
	s_add_i32 s26, s19, 8
	s_add_i32 s28, s19, 12
	s_add_i32 s31, s20, 16
	v_lshlrev_b64 v[48:49], 12, v[48:49]
	v_lshl_add_u64 v[64:65], v[34:35], 0, v[64:65]
	v_lshl_add_u64 v[50:51], v[34:35], 0, v[50:51]
	v_lshlrev_b64 v[68:69], 12, v[4:5]
	v_or_b32_e32 v4, s29, v36
	v_mov_b32_e32 v53, v5
	v_mov_b32_e32 v55, v5
	s_add_i32 s35, s20, 20
	v_or_b32_e32 v52, s26, v3
	v_or_b32_e32 v54, s28, v3
	v_lshl_add_u64 v[48:49], v[34:35], 0, v[48:49]
	v_lshl_add_u64 v[66:67], v[34:35], 0, v[66:67]
	global_load_dword v47, v[64:65], off
	global_load_dword v80, v[48:49], off
	global_load_dword v81, v[66:67], off
	global_load_dword v82, v[50:51], off
	v_lshlrev_b64 v[50:51], 12, v[4:5]
	v_or_b32_e32 v4, s31, v36
	s_add_i32 s30, s19, 16
	s_add_i32 s34, s19, 20
	s_add_i32 s37, s20, 24
	v_lshlrev_b64 v[52:53], 12, v[52:53]
	v_lshlrev_b64 v[54:55], 12, v[54:55]
	v_lshl_add_u64 v[48:49], v[34:35], 0, v[68:69]
	v_lshl_add_u64 v[50:51], v[34:35], 0, v[50:51]
	v_lshlrev_b64 v[64:65], 12, v[4:5]
	v_or_b32_e32 v4, s35, v36
	v_mov_b32_e32 v57, v5
	v_mov_b32_e32 v59, v5
	s_add_i32 s36, s19, 24
	s_add_i32 s38, s19, 28
	s_add_i32 s39, s20, 28
	v_or_b32_e32 v56, s30, v3
	v_or_b32_e32 v58, s34, v3
	v_lshl_add_u64 v[52:53], v[34:35], 0, v[52:53]
	v_lshl_add_u64 v[54:55], v[34:35], 0, v[54:55]
	global_load_dword v83, v[48:49], off
	global_load_dword v84, v[52:53], off
	global_load_dword v85, v[50:51], off
	global_load_dword v86, v[54:55], off
	v_lshlrev_b64 v[50:51], 12, v[4:5]
	v_or_b32_e32 v4, s37, v36
	v_mov_b32_e32 v61, v5
	v_mov_b32_e32 v63, v5
	v_or_b32_e32 v60, s36, v3
	v_or_b32_e32 v62, s38, v3
	v_lshlrev_b64 v[56:57], 12, v[56:57]
	v_lshlrev_b64 v[58:59], 12, v[58:59]
	v_lshl_add_u64 v[48:49], v[34:35], 0, v[64:65]
	v_lshl_add_u64 v[50:51], v[34:35], 0, v[50:51]
	v_lshlrev_b64 v[52:53], 12, v[4:5]
	v_or_b32_e32 v4, s39, v36
	v_lshlrev_b64 v[60:61], 12, v[60:61]
	v_lshlrev_b64 v[62:63], 12, v[62:63]
	v_lshl_add_u64 v[56:57], v[34:35], 0, v[56:57]
	v_lshl_add_u64 v[58:59], v[34:35], 0, v[58:59]
	global_load_dword v87, v[48:49], off
	global_load_dword v88, v[56:57], off
	global_load_dword v89, v[50:51], off
	global_load_dword v90, v[58:59], off
	v_lshl_add_u64 v[48:49], v[34:35], 0, v[52:53]
	v_lshlrev_b64 v[50:51], 12, v[4:5]
	v_lshl_add_u64 v[60:61], v[34:35], 0, v[60:61]
	v_lshl_add_u64 v[62:63], v[34:35], 0, v[62:63]
	v_lshl_add_u64 v[50:51], v[34:35], 0, v[50:51]
	global_load_dword v4, v[48:49], off
	global_load_dword v91, v[60:61], off
	global_load_dword v92, v[50:51], off
	global_load_dword v93, v[62:63], off
	v_or_b32_e32 v50, s19, v1
	v_or_b32_e32 v48, s20, v2
	s_add_i32 s4, s4, 16
	s_add_i32 s3, s3, 16
	s_add_i32 s13, s13, -16
	v_mad_u64_u32 v[48:49], s[20:21], v48, s14, v[8:9]
	v_mad_u64_u32 v[50:51], s[20:21], v50, s14, v[8:9]
	v_or_b32_e32 v49, s22, v1
	v_or_b32_e32 v51, s23, v2
	v_or_b32_e32 v58, s26, v1
	v_or_b32_e32 v56, s27, v2
	v_or_b32_e32 v62, s28, v1
	v_or_b32_e32 v60, s29, v2
	v_or_b32_e32 v66, s30, v1
	v_or_b32_e32 v64, s31, v2
	v_or_b32_e32 v70, s34, v1
	v_or_b32_e32 v68, s35, v2
	v_or_b32_e32 v74, s36, v1
	v_or_b32_e32 v72, s37, v2
	v_or_b32_e32 v78, s38, v1
	v_or_b32_e32 v76, s39, v2
	s_cmp_lg_u32 s13, 0
	v_mad_u64_u32 v[52:53], s[20:21], v51, s14, v[8:9]
	v_mad_u64_u32 v[54:55], s[20:21], v49, s14, v[8:9]
	v_mad_u64_u32 v[56:57], s[20:21], v56, s14, v[8:9]
	v_mad_u64_u32 v[58:59], s[20:21], v58, s14, v[8:9]
	v_mad_u64_u32 v[60:61], s[20:21], v60, s14, v[8:9]
	v_mad_u64_u32 v[62:63], s[20:21], v62, s14, v[8:9]
	v_mad_u64_u32 v[64:65], s[20:21], v64, s14, v[8:9]
	v_mad_u64_u32 v[66:67], s[20:21], v66, s14, v[8:9]
	v_mad_u64_u32 v[68:69], s[20:21], v68, s14, v[8:9]
	v_mad_u64_u32 v[70:71], s[20:21], v70, s14, v[8:9]
	v_mad_u64_u32 v[72:73], s[20:21], v72, s14, v[8:9]
	v_mad_u64_u32 v[74:75], s[20:21], v74, s14, v[8:9]
	v_mad_u64_u32 v[76:77], s[20:21], v76, s14, v[8:9]
	v_mad_u64_u32 v[78:79], s[20:21], v78, s14, v[8:9]
	v_mov_b32_e32 v125, v5
	s_lshl_b32 s19, s3, 1
	s_lshl_b32 s20, s4, 1
	v_or_b32_e32 v124, s20, v36
	s_add_i32 s22, s19, 4
	s_add_i32 s23, s20, 4
	v_mov_b32_e32 v131, v125
	s_add_i32 s27, s20, 8
	v_lshlrev_b64 v[144:145], 12, v[124:125]
	v_or_b32_e32 v130, s22, v3
	v_or_b32_e32 v124, s23, v36
	v_mov_b32_e32 v129, v125
	v_or_b32_e32 v128, s19, v3
	s_add_i32 s29, s20, 12
	v_lshlrev_b64 v[130:131], 12, v[130:131]
	v_lshlrev_b64 v[146:147], 12, v[124:125]
	v_or_b32_e32 v124, s27, v36
	s_add_i32 s26, s19, 8
	s_add_i32 s28, s19, 12
	s_add_i32 s31, s20, 16
	v_lshlrev_b64 v[128:129], 12, v[128:129]
	v_lshl_add_u64 v[144:145], v[34:35], 0, v[144:145]
	v_lshl_add_u64 v[130:131], v[34:35], 0, v[130:131]
	v_lshlrev_b64 v[148:149], 12, v[124:125]
	v_or_b32_e32 v124, s29, v36
	v_mov_b32_e32 v133, v125
	v_mov_b32_e32 v135, v125
	s_add_i32 s35, s20, 20
	v_or_b32_e32 v132, s26, v3
	v_or_b32_e32 v134, s28, v3
	v_lshl_add_u64 v[128:129], v[34:35], 0, v[128:129]
	v_lshl_add_u64 v[146:147], v[34:35], 0, v[146:147]
	global_load_dword v127, v[144:145], off
	global_load_dword v160, v[128:129], off
	global_load_dword v161, v[146:147], off
	global_load_dword v178, v[130:131], off
	v_lshlrev_b64 v[130:131], 12, v[124:125]
	v_or_b32_e32 v124, s31, v36
	s_add_i32 s30, s19, 16
	s_add_i32 s34, s19, 20
	s_add_i32 s37, s20, 24
	v_lshlrev_b64 v[132:133], 12, v[132:133]
	v_lshlrev_b64 v[134:135], 12, v[134:135]
	v_lshl_add_u64 v[128:129], v[34:35], 0, v[148:149]
	v_lshl_add_u64 v[130:131], v[34:35], 0, v[130:131]
	v_lshlrev_b64 v[144:145], 12, v[124:125]
	v_or_b32_e32 v124, s35, v36
	v_mov_b32_e32 v137, v125
	v_mov_b32_e32 v139, v125
	s_add_i32 s36, s19, 24
	s_add_i32 s38, s19, 28
	s_add_i32 s39, s20, 28
	v_or_b32_e32 v136, s30, v3
	v_or_b32_e32 v138, s34, v3
	v_lshl_add_u64 v[132:133], v[34:35], 0, v[132:133]
	v_lshl_add_u64 v[134:135], v[34:35], 0, v[134:135]
	global_load_dword v179, v[128:129], off
	global_load_dword v180, v[132:133], off
	global_load_dword v181, v[130:131], off
	global_load_dword v182, v[134:135], off
	v_lshlrev_b64 v[130:131], 12, v[124:125]
	v_or_b32_e32 v124, s37, v36
	v_mov_b32_e32 v141, v125
	v_mov_b32_e32 v143, v125
	v_or_b32_e32 v140, s36, v3
	v_or_b32_e32 v142, s38, v3
	v_lshlrev_b64 v[136:137], 12, v[136:137]
	v_lshlrev_b64 v[138:139], 12, v[138:139]
	v_lshl_add_u64 v[128:129], v[34:35], 0, v[144:145]
	v_lshl_add_u64 v[130:131], v[34:35], 0, v[130:131]
	v_lshlrev_b64 v[132:133], 12, v[124:125]
	v_or_b32_e32 v124, s39, v36
	v_lshlrev_b64 v[140:141], 12, v[140:141]
	v_lshlrev_b64 v[142:143], 12, v[142:143]
	v_lshl_add_u64 v[136:137], v[34:35], 0, v[136:137]
	v_lshl_add_u64 v[138:139], v[34:35], 0, v[138:139]
	global_load_dword v183, v[128:129], off
	global_load_dword v184, v[136:137], off
	global_load_dword v185, v[130:131], off
	global_load_dword v186, v[138:139], off
	v_lshl_add_u64 v[128:129], v[34:35], 0, v[132:133]
	v_lshlrev_b64 v[130:131], 12, v[124:125]
	v_lshl_add_u64 v[140:141], v[34:35], 0, v[140:141]
	v_lshl_add_u64 v[142:143], v[34:35], 0, v[142:143]
	v_lshl_add_u64 v[130:131], v[34:35], 0, v[130:131]
	global_load_dword v124, v[128:129], off
	global_load_dword v187, v[140:141], off
	global_load_dword v188, v[130:131], off
	global_load_dword v189, v[142:143], off
	v_or_b32_e32 v130, s19, v1
	v_or_b32_e32 v128, s20, v2
	s_add_i32 s4, s4, 16
	s_add_i32 s3, s3, 16
	s_add_i32 s13, s13, -16
	v_mad_u64_u32 v[128:129], s[20:21], v128, s14, v[8:9]
	v_mad_u64_u32 v[130:131], s[20:21], v130, s14, v[8:9]
	v_or_b32_e32 v129, s22, v1
	v_or_b32_e32 v131, s23, v2
	v_or_b32_e32 v138, s26, v1
	v_or_b32_e32 v136, s27, v2
	v_or_b32_e32 v142, s28, v1
	v_or_b32_e32 v140, s29, v2
	v_or_b32_e32 v146, s30, v1
	v_or_b32_e32 v144, s31, v2
	v_or_b32_e32 v150, s34, v1
	v_or_b32_e32 v148, s35, v2
	v_or_b32_e32 v154, s36, v1
	v_or_b32_e32 v152, s37, v2
	v_or_b32_e32 v158, s38, v1
	v_or_b32_e32 v156, s39, v2
	s_cmp_lg_u32 s13, 0
	v_mad_u64_u32 v[132:133], s[20:21], v131, s14, v[8:9]
	v_mad_u64_u32 v[134:135], s[20:21], v129, s14, v[8:9]
	v_mad_u64_u32 v[136:137], s[20:21], v136, s14, v[8:9]
	v_mad_u64_u32 v[138:139], s[20:21], v138, s14, v[8:9]
	v_mad_u64_u32 v[140:141], s[20:21], v140, s14, v[8:9]
	v_mad_u64_u32 v[142:143], s[20:21], v142, s14, v[8:9]
	v_mad_u64_u32 v[144:145], s[20:21], v144, s14, v[8:9]
	v_mad_u64_u32 v[146:147], s[20:21], v146, s14, v[8:9]
	v_mad_u64_u32 v[148:149], s[20:21], v148, s14, v[8:9]
	v_mad_u64_u32 v[150:151], s[20:21], v150, s14, v[8:9]
	v_mad_u64_u32 v[152:153], s[20:21], v152, s14, v[8:9]
	v_mad_u64_u32 v[154:155], s[20:21], v154, s14, v[8:9]
	v_mad_u64_u32 v[156:157], s[20:21], v156, s14, v[8:9]
	v_mad_u64_u32 v[158:159], s[20:21], v158, s14, v[8:9]
	s_waitcnt vmcnt(31)
	ds_write_b32 v48, v47
	s_waitcnt vmcnt(30)
	ds_write_b32 v50, v80
	s_waitcnt vmcnt(29)
	ds_write_b32 v52, v81
	s_waitcnt vmcnt(28)
	ds_write_b32 v54, v82
	s_waitcnt vmcnt(27)
	ds_write_b32 v56, v83
	s_waitcnt vmcnt(26)
	ds_write_b32 v58, v84
	s_waitcnt vmcnt(25)
	ds_write_b32 v60, v85
	s_waitcnt vmcnt(24)
	ds_write_b32 v62, v86
	s_waitcnt vmcnt(23)
	ds_write_b32 v64, v87
	s_waitcnt vmcnt(22)
	ds_write_b32 v66, v88
	s_waitcnt vmcnt(21)
	ds_write_b32 v68, v89
	s_waitcnt vmcnt(20)
	ds_write_b32 v70, v90
	s_waitcnt vmcnt(19)
	ds_write_b32 v72, v4
	s_waitcnt vmcnt(18)
	ds_write_b32 v74, v91
	s_waitcnt vmcnt(17)
	ds_write_b32 v76, v92
	s_waitcnt vmcnt(16)
	ds_write_b32 v78, v93
	s_waitcnt vmcnt(15)
	ds_write_b32 v128, v127
	s_waitcnt vmcnt(14)
	ds_write_b32 v130, v160
	s_waitcnt vmcnt(13)
	ds_write_b32 v132, v161
	s_waitcnt vmcnt(12)
	ds_write_b32 v134, v178
	s_waitcnt vmcnt(11)
	ds_write_b32 v136, v179
	s_waitcnt vmcnt(10)
	ds_write_b32 v138, v180
	s_waitcnt vmcnt(9)
	ds_write_b32 v140, v181
	s_waitcnt vmcnt(8)
	ds_write_b32 v142, v182
	s_waitcnt vmcnt(7)
	ds_write_b32 v144, v183
	s_waitcnt vmcnt(6)
	ds_write_b32 v146, v184
	s_waitcnt vmcnt(5)
	ds_write_b32 v148, v185
	s_waitcnt vmcnt(4)
	ds_write_b32 v150, v186
	s_waitcnt vmcnt(3)
	ds_write_b32 v152, v124
	s_waitcnt vmcnt(2)
	ds_write_b32 v154, v187
	s_waitcnt vmcnt(1)
	ds_write_b32 v156, v188
	s_waitcnt vmcnt(0)
	ds_write_b32 v158, v189
	s_and_b32 s3, s12, 0x300
	s_and_b32 s12, s12, 0xe0
	v_or_b32_e32 v4, s12, v37
	s_lshl_b32 s4, s2, 1
	v_lshlrev_b32_e32 v4, 2, v4
	s_lshl_b32 s2, s18, 4
	v_or_b32_e32 v3, s3, v38
	v_and_b32_e32 v4, 0x90, v4
	s_and_b32 s2, s2, 0x60
	v_or3_b32 v4, s2, v4, v3
	v_mul_u32_u24_e32 v4, 0xb00, v4
	s_waitcnt lgkmcnt(0)
	v_lshl_add_u64 v[66:67], v[24:25], 0, s[4:5]
	v_lshlrev_b32_e32 v4, 1, v4
	ds_read2_b32 v[34:35], v40 offset0:33 offset1:41
	ds_read2_b32 v[52:53], v40 offset1:8
	ds_read2_b32 v[54:55], v40 offset0:66 offset1:74
	ds_read2_b32 v[56:57], v40 offset0:99 offset1:107
	ds_read2_b32 v[58:59], v40 offset0:132 offset1:140
	ds_read2_b32 v[60:61], v40 offset0:165 offset1:173
	ds_read2_b32 v[62:63], v40 offset0:198 offset1:206
	ds_read2_b32 v[64:65], v40 offset0:231 offset1:239
	v_lshl_add_u64 v[68:69], v[66:67], 0, v[4:5]
	v_or_b32_e32 v4, s12, v41
	s_waitcnt lgkmcnt(6)
	v_cvt_pk_bf16_f32 v48, v52, v34
	v_lshlrev_b32_e32 v34, 2, v4
	v_lshrrev_b32_e32 v4, 1, v4
	v_and_b32_e32 v34, 0x90, v34
	v_and_b32_e32 v4, 0x64, v4
	v_or3_b32 v4, v4, v34, v3
	v_mul_u32_u24_e32 v4, 0xb00, v4
	s_waitcnt lgkmcnt(4)
	v_cvt_pk_bf16_f32 v49, v54, v56
	s_waitcnt lgkmcnt(2)
	v_cvt_pk_bf16_f32 v50, v58, v60
	s_waitcnt lgkmcnt(0)
	v_cvt_pk_bf16_f32 v51, v62, v64
	v_lshlrev_b32_e32 v4, 1, v4
	global_store_dwordx4 v[68:69], v[48:51], off
	s_mov_b64 s[2:3], 0
	s_nop 0
	v_cvt_pk_bf16_f32 v48, v53, v35
	v_cvt_pk_bf16_f32 v49, v55, v57
	v_cvt_pk_bf16_f32 v50, v59, v61
	v_cvt_pk_bf16_f32 v51, v63, v65
	v_lshl_add_u64 v[34:35], v[66:67], 0, v[4:5]
	v_or_b32_e32 v4, s12, v42
	ds_read2_b32 v[52:53], v40 offset0:16 offset1:24
	ds_read2_b32 v[54:55], v40 offset0:49 offset1:57
	ds_read2_b32 v[56:57], v40 offset0:82 offset1:90
	ds_read2_b32 v[58:59], v40 offset0:115 offset1:123
	ds_read2_b32 v[60:61], v40 offset0:148 offset1:156
	ds_read2_b32 v[62:63], v40 offset0:181 offset1:189
	ds_read2_b32 v[64:65], v40 offset0:214 offset1:222
	ds_read2_b32 v[68:69], v40 offset0:247 offset1:255
	global_store_dwordx4 v[34:35], v[48:51], off
	v_lshlrev_b32_e32 v34, 2, v4
	v_lshrrev_b32_e32 v4, 1, v4
	v_and_b32_e32 v34, 0x90, v34
	v_and_b32_e32 v4, 0x68, v4
	v_or3_b32 v4, v4, v34, v3
	v_mul_u32_u24_e32 v4, 0xb00, v4
	v_lshlrev_b32_e32 v4, 1, v4
	s_waitcnt lgkmcnt(6)
	v_cvt_pk_bf16_f32 v48, v52, v54
	s_waitcnt lgkmcnt(4)
	v_cvt_pk_bf16_f32 v49, v56, v58
	s_waitcnt lgkmcnt(2)
	v_cvt_pk_bf16_f32 v50, v60, v62
	s_waitcnt lgkmcnt(0)
	v_cvt_pk_bf16_f32 v51, v64, v68
	v_lshl_add_u64 v[34:35], v[66:67], 0, v[4:5]
	v_or_b32_e32 v4, s12, v43
	global_store_dwordx4 v[34:35], v[48:51], off
	v_lshlrev_b32_e32 v34, 2, v4
	v_lshrrev_b32_e32 v4, 1, v4
	v_and_b32_e32 v34, 0x90, v34
	v_and_b32_e32 v4, 0x6c, v4
	v_or3_b32 v3, v4, v34, v3
	v_mul_u32_u24_e32 v3, 0xb00, v3
	v_lshlrev_b32_e32 v4, 1, v3
	v_cvt_pk_bf16_f32 v48, v53, v55
	v_cvt_pk_bf16_f32 v49, v57, v59
	v_cvt_pk_bf16_f32 v50, v61, v63
	v_cvt_pk_bf16_f32 v51, v65, v69
	v_lshl_add_u64 v[34:35], v[66:67], 0, v[4:5]
	global_store_dwordx4 v[34:35], v[48:51], off
	s_waitcnt lgkmcnt(0)

.LBB0_22:
	s_lshl_b32 s21, s13, 1
	s_lshl_b32 s22, s19, 1
	v_or_b32_e32 v3, s21, v1
	v_or_b32_e32 v36, s22, v2
	s_add_i32 s23, s21, 4
	s_add_i32 s26, s22, 4
	s_add_i32 s27, s21, 8
	s_add_i32 s28, s22, 8
	s_add_i32 s29, s21, 12
	s_add_i32 s30, s22, 12
	s_add_i32 s31, s21, 16
	s_add_i32 s34, s22, 16
	s_add_i32 s35, s21, 20
	s_add_i32 s36, s22, 20
	s_add_i32 s37, s21, 24
	s_add_i32 s38, s22, 24
	s_add_i32 s21, s21, 28
	s_add_i32 s22, s22, 28
	v_add_u32_e32 v47, s4, v36
	v_or_b32_e32 v78, s23, v1
	v_or_b32_e32 v79, s26, v2
	v_or_b32_e32 v80, s27, v1
	v_or_b32_e32 v81, s28, v2
	v_or_b32_e32 v82, s29, v1
	v_or_b32_e32 v83, s30, v2
	v_or_b32_e32 v84, s31, v1
	v_or_b32_e32 v85, s34, v2
	v_or_b32_e32 v86, s35, v1
	v_or_b32_e32 v87, s36, v2
	v_or_b32_e32 v88, s37, v1
	v_or_b32_e32 v89, s38, v2
	v_or_b32_e32 v90, s21, v1
	v_or_b32_e32 v91, s22, v2
	v_add_u32_e32 v34, s12, v3
	v_mad_u64_u32 v[48:49], s[22:23], v47, s15, v[4:5]
	v_add_u32_e32 v47, s4, v79
	v_add_u32_e32 v50, s12, v78
	v_add_u32_e32 v56, s4, v81
	v_add_u32_e32 v54, s12, v80
	v_add_u32_e32 v60, s4, v83
	v_add_u32_e32 v58, s12, v82
	v_add_u32_e32 v64, s4, v85
	v_add_u32_e32 v62, s12, v84
	v_add_u32_e32 v68, s4, v87
	v_add_u32_e32 v66, s12, v86
	v_add_u32_e32 v72, s4, v89
	v_add_u32_e32 v70, s12, v88
	v_add_u32_e32 v76, s4, v91
	v_add_u32_e32 v74, s12, v90
	v_mad_u64_u32 v[34:35], s[22:23], v34, s15, v[4:5]
	v_mov_b32_e32 v49, v5
	v_mad_u64_u32 v[50:51], s[22:23], v50, s15, v[4:5]
	v_mad_u64_u32 v[52:53], s[22:23], v47, s15, v[4:5]
	v_mad_u64_u32 v[54:55], s[22:23], v54, s15, v[4:5]
	v_mad_u64_u32 v[56:57], s[22:23], v56, s15, v[4:5]
	v_mad_u64_u32 v[58:59], s[22:23], v58, s15, v[4:5]
	v_mad_u64_u32 v[60:61], s[22:23], v60, s15, v[4:5]
	v_mad_u64_u32 v[62:63], s[22:23], v62, s15, v[4:5]
	v_mad_u64_u32 v[64:65], s[22:23], v64, s15, v[4:5]
	v_mad_u64_u32 v[66:67], s[22:23], v66, s15, v[4:5]
	v_mad_u64_u32 v[68:69], s[22:23], v68, s15, v[4:5]
	v_mad_u64_u32 v[70:71], s[22:23], v70, s15, v[4:5]
	v_mad_u64_u32 v[72:73], s[22:23], v72, s15, v[4:5]
	v_mad_u64_u32 v[74:75], s[22:23], v74, s15, v[4:5]
	v_mad_u64_u32 v[76:77], s[22:23], v76, s15, v[4:5]
	v_mov_b32_e32 v35, v5
	v_lshl_add_u64 v[48:49], v[48:49], 2, s[70:71]
	v_mov_b32_e32 v53, v5
	v_mov_b32_e32 v51, v5
	v_mov_b32_e32 v57, v5
	v_mov_b32_e32 v55, v5
	v_mov_b32_e32 v61, v5
	v_mov_b32_e32 v59, v5
	v_mov_b32_e32 v65, v5
	v_mov_b32_e32 v63, v5
	v_mov_b32_e32 v69, v5
	v_mov_b32_e32 v67, v5
	v_mov_b32_e32 v73, v5
	v_mov_b32_e32 v71, v5
	v_mov_b32_e32 v77, v5
	v_mov_b32_e32 v75, v5
	v_lshl_add_u64 v[34:35], v[34:35], 2, s[70:71]
	v_lshl_add_u64 v[52:53], v[52:53], 2, s[70:71]
	v_lshl_add_u64 v[50:51], v[50:51], 2, s[70:71]
	v_lshl_add_u64 v[56:57], v[56:57], 2, s[70:71]
	v_lshl_add_u64 v[54:55], v[54:55], 2, s[70:71]
	v_lshl_add_u64 v[60:61], v[60:61], 2, s[70:71]
	v_lshl_add_u64 v[58:59], v[58:59], 2, s[70:71]
	v_lshl_add_u64 v[64:65], v[64:65], 2, s[70:71]
	v_lshl_add_u64 v[62:63], v[62:63], 2, s[70:71]
	v_lshl_add_u64 v[68:69], v[68:69], 2, s[70:71]
	v_lshl_add_u64 v[66:67], v[66:67], 2, s[70:71]
	v_lshl_add_u64 v[72:73], v[72:73], 2, s[70:71]
	v_lshl_add_u64 v[70:71], v[70:71], 2, s[70:71]
	v_lshl_add_u64 v[76:77], v[76:77], 2, s[70:71]
	v_lshl_add_u64 v[74:75], v[74:75], 2, s[70:71]
	global_load_dword v47, v[48:49], off
	global_load_dword v92, v[34:35], off
	global_load_dword v93, v[52:53], off
	global_load_dword v94, v[50:51], off
	global_load_dword v95, v[56:57], off
	global_load_dword v96, v[54:55], off
	global_load_dword v97, v[60:61], off
	global_load_dword v98, v[58:59], off
	global_load_dword v99, v[64:65], off
	global_load_dword v100, v[62:63], off
	global_load_dword v101, v[68:69], off
	global_load_dword v102, v[66:67], off
	global_load_dword v103, v[72:73], off
	global_load_dword v104, v[70:71], off
	global_load_dword v105, v[76:77], off
	global_load_dword v106, v[74:75], off
	s_add_i32 s19, s19, 16
	s_add_i32 s13, s13, 16
	s_add_i32 s20, s20, -16
	v_mad_u64_u32 v[34:35], s[22:23], v36, s14, v[8:9]
	s_cmp_lg_u32 s20, 0
	v_mad_u64_u32 v[48:49], s[22:23], v3, s14, v[8:9]
	v_mad_u64_u32 v[50:51], s[22:23], v79, s14, v[8:9]
	v_mad_u64_u32 v[52:53], s[22:23], v78, s14, v[8:9]
	v_mad_u64_u32 v[54:55], s[22:23], v81, s14, v[8:9]
	v_mad_u64_u32 v[56:57], s[22:23], v80, s14, v[8:9]
	v_mad_u64_u32 v[58:59], s[22:23], v83, s14, v[8:9]
	v_mad_u64_u32 v[60:61], s[22:23], v82, s14, v[8:9]
	v_mad_u64_u32 v[62:63], s[22:23], v85, s14, v[8:9]
	v_mad_u64_u32 v[64:65], s[22:23], v84, s14, v[8:9]
	v_mad_u64_u32 v[66:67], s[22:23], v87, s14, v[8:9]
	v_mad_u64_u32 v[68:69], s[22:23], v86, s14, v[8:9]
	v_mad_u64_u32 v[70:71], s[22:23], v89, s14, v[8:9]
	v_mad_u64_u32 v[72:73], s[22:23], v88, s14, v[8:9]
	v_mad_u64_u32 v[74:75], s[22:23], v91, s14, v[8:9]
	v_mad_u64_u32 v[76:77], s[22:23], v90, s14, v[8:9]
	v_mov_b32_e32 v124, v2
	s_lshl_b32 s21, s13, 1
	s_lshl_b32 s22, s19, 1
	v_or_b32_e32 v125, s21, v1
	v_or_b32_e32 v128, s22, v124
	s_add_i32 s23, s21, 4
	s_add_i32 s26, s22, 4
	s_add_i32 s27, s21, 8
	s_add_i32 s28, s22, 8
	s_add_i32 s29, s21, 12
	s_add_i32 s30, s22, 12
	s_add_i32 s31, s21, 16
	s_add_i32 s34, s22, 16
	s_add_i32 s35, s21, 20
	s_add_i32 s36, s22, 20
	s_add_i32 s37, s21, 24
	s_add_i32 s38, s22, 24
	s_add_i32 s21, s21, 28
	s_add_i32 s22, s22, 28
	v_add_u32_e32 v131, s4, v128
	v_or_b32_e32 v178, s23, v1
	v_or_b32_e32 v179, s26, v124
	v_or_b32_e32 v180, s27, v1
	v_or_b32_e32 v181, s28, v124
	v_or_b32_e32 v182, s29, v1
	v_or_b32_e32 v183, s30, v124
	v_or_b32_e32 v184, s31, v1
	v_or_b32_e32 v185, s34, v124
	v_or_b32_e32 v186, s35, v1
	v_or_b32_e32 v187, s36, v124
	v_or_b32_e32 v188, s37, v1
	v_or_b32_e32 v189, s38, v124
	v_or_b32_e32 v190, s21, v1
	v_or_b32_e32 v191, s22, v124
	v_add_u32_e32 v126, s12, v125
	v_mad_u64_u32 v[132:133], s[22:23], v131, s15, v[4:5]
	v_add_u32_e32 v131, s4, v179
	v_add_u32_e32 v134, s12, v178
	v_add_u32_e32 v140, s4, v181
	v_add_u32_e32 v138, s12, v180
	v_add_u32_e32 v144, s4, v183
	v_add_u32_e32 v142, s12, v182
	v_add_u32_e32 v148, s4, v185
	v_add_u32_e32 v146, s12, v184
	v_add_u32_e32 v152, s4, v187
	v_add_u32_e32 v150, s12, v186
	v_add_u32_e32 v156, s4, v189
	v_add_u32_e32 v154, s12, v188
	v_add_u32_e32 v160, s4, v191
	v_add_u32_e32 v158, s12, v190
	v_mad_u64_u32 v[126:127], s[22:23], v126, s15, v[4:5]
	v_mov_b32_e32 v133, v5
	v_mad_u64_u32 v[134:135], s[22:23], v134, s15, v[4:5]
	v_mad_u64_u32 v[136:137], s[22:23], v131, s15, v[4:5]
	v_mad_u64_u32 v[138:139], s[22:23], v138, s15, v[4:5]
	v_mad_u64_u32 v[140:141], s[22:23], v140, s15, v[4:5]
	v_mad_u64_u32 v[142:143], s[22:23], v142, s15, v[4:5]
	v_mad_u64_u32 v[144:145], s[22:23], v144, s15, v[4:5]
	v_mad_u64_u32 v[146:147], s[22:23], v146, s15, v[4:5]
	v_mad_u64_u32 v[148:149], s[22:23], v148, s15, v[4:5]
	v_mad_u64_u32 v[150:151], s[22:23], v150, s15, v[4:5]
	v_mad_u64_u32 v[152:153], s[22:23], v152, s15, v[4:5]
	v_mad_u64_u32 v[154:155], s[22:23], v154, s15, v[4:5]
	v_mad_u64_u32 v[156:157], s[22:23], v156, s15, v[4:5]
	v_mad_u64_u32 v[158:159], s[22:23], v158, s15, v[4:5]
	v_mad_u64_u32 v[160:161], s[22:23], v160, s15, v[4:5]
	v_mov_b32_e32 v127, v5
	v_lshl_add_u64 v[132:133], v[132:133], 2, s[70:71]
	v_mov_b32_e32 v137, v5
	v_mov_b32_e32 v135, v5
	v_mov_b32_e32 v141, v5
	v_mov_b32_e32 v139, v5
	v_mov_b32_e32 v145, v5
	v_mov_b32_e32 v143, v5
	v_mov_b32_e32 v149, v5
	v_mov_b32_e32 v147, v5
	v_mov_b32_e32 v153, v5
	v_mov_b32_e32 v151, v5
	v_mov_b32_e32 v157, v5
	v_mov_b32_e32 v155, v5
	v_mov_b32_e32 v161, v5
	v_mov_b32_e32 v159, v5
	v_lshl_add_u64 v[126:127], v[126:127], 2, s[70:71]
	v_lshl_add_u64 v[136:137], v[136:137], 2, s[70:71]
	v_lshl_add_u64 v[134:135], v[134:135], 2, s[70:71]
	v_lshl_add_u64 v[140:141], v[140:141], 2, s[70:71]
	v_lshl_add_u64 v[138:139], v[138:139], 2, s[70:71]
	v_lshl_add_u64 v[144:145], v[144:145], 2, s[70:71]
	v_lshl_add_u64 v[142:143], v[142:143], 2, s[70:71]
	v_lshl_add_u64 v[148:149], v[148:149], 2, s[70:71]
	v_lshl_add_u64 v[146:147], v[146:147], 2, s[70:71]
	v_lshl_add_u64 v[152:153], v[152:153], 2, s[70:71]
	v_lshl_add_u64 v[150:151], v[150:151], 2, s[70:71]
	v_lshl_add_u64 v[156:157], v[156:157], 2, s[70:71]
	v_lshl_add_u64 v[154:155], v[154:155], 2, s[70:71]
	v_lshl_add_u64 v[160:161], v[160:161], 2, s[70:71]
	v_lshl_add_u64 v[158:159], v[158:159], 2, s[70:71]
	global_load_dword v131, v[132:133], off
	global_load_dword v192, v[126:127], off
	global_load_dword v193, v[136:137], off
	global_load_dword v194, v[134:135], off
	global_load_dword v195, v[140:141], off
	global_load_dword v196, v[138:139], off
	global_load_dword v197, v[144:145], off
	global_load_dword v198, v[142:143], off
	global_load_dword v199, v[148:149], off
	global_load_dword v200, v[146:147], off
	global_load_dword v201, v[152:153], off
	global_load_dword v202, v[150:151], off
	global_load_dword v203, v[156:157], off
	global_load_dword v204, v[154:155], off
	global_load_dword v205, v[160:161], off
	global_load_dword v206, v[158:159], off
	s_add_i32 s19, s19, 16
	s_add_i32 s13, s13, 16
	s_add_i32 s20, s20, -16
	v_mad_u64_u32 v[126:127], s[22:23], v128, s14, v[8:9]
	s_cmp_lg_u32 s20, 0
	v_mad_u64_u32 v[132:133], s[22:23], v125, s14, v[8:9]
	v_mad_u64_u32 v[134:135], s[22:23], v179, s14, v[8:9]
	v_mad_u64_u32 v[136:137], s[22:23], v178, s14, v[8:9]
	v_mad_u64_u32 v[138:139], s[22:23], v181, s14, v[8:9]
	v_mad_u64_u32 v[140:141], s[22:23], v180, s14, v[8:9]
	v_mad_u64_u32 v[142:143], s[22:23], v183, s14, v[8:9]
	v_mad_u64_u32 v[144:145], s[22:23], v182, s14, v[8:9]
	v_mad_u64_u32 v[146:147], s[22:23], v185, s14, v[8:9]
	v_mad_u64_u32 v[148:149], s[22:23], v184, s14, v[8:9]
	v_mad_u64_u32 v[150:151], s[22:23], v187, s14, v[8:9]
	v_mad_u64_u32 v[152:153], s[22:23], v186, s14, v[8:9]
	v_mad_u64_u32 v[154:155], s[22:23], v189, s14, v[8:9]
	v_mad_u64_u32 v[156:157], s[22:23], v188, s14, v[8:9]
	v_mad_u64_u32 v[158:159], s[22:23], v191, s14, v[8:9]
	v_mad_u64_u32 v[160:161], s[22:23], v190, s14, v[8:9]
	s_waitcnt vmcnt(31)
	ds_write_b32 v34, v47
	s_waitcnt vmcnt(30)
	ds_write_b32 v48, v92
	s_waitcnt vmcnt(29)
	ds_write_b32 v50, v93
	s_waitcnt vmcnt(28)
	ds_write_b32 v52, v94
	s_waitcnt vmcnt(27)
	ds_write_b32 v54, v95
	s_waitcnt vmcnt(26)
	ds_write_b32 v56, v96
	s_waitcnt vmcnt(25)
	ds_write_b32 v58, v97
	s_waitcnt vmcnt(24)
	ds_write_b32 v60, v98
	s_waitcnt vmcnt(23)
	ds_write_b32 v62, v99
	s_waitcnt vmcnt(22)
	ds_write_b32 v64, v100
	s_waitcnt vmcnt(21)
	ds_write_b32 v66, v101
	s_waitcnt vmcnt(20)
	ds_write_b32 v68, v102
	s_waitcnt vmcnt(19)
	ds_write_b32 v70, v103
	s_waitcnt vmcnt(18)
	ds_write_b32 v72, v104
	s_waitcnt vmcnt(17)
	ds_write_b32 v74, v105
	s_waitcnt vmcnt(16)
	ds_write_b32 v76, v106
	s_waitcnt vmcnt(15)
	ds_write_b32 v126, v131
	s_waitcnt vmcnt(14)
	ds_write_b32 v132, v192
	s_waitcnt vmcnt(13)
	ds_write_b32 v134, v193
	s_waitcnt vmcnt(12)
	ds_write_b32 v136, v194
	s_waitcnt vmcnt(11)
	ds_write_b32 v138, v195
	s_waitcnt vmcnt(10)
	ds_write_b32 v140, v196
	s_waitcnt vmcnt(9)
	ds_write_b32 v142, v197
	s_waitcnt vmcnt(8)
	ds_write_b32 v144, v198
	s_waitcnt vmcnt(7)
	ds_write_b32 v146, v199
	s_waitcnt vmcnt(6)
	ds_write_b32 v148, v200
	s_waitcnt vmcnt(5)
	ds_write_b32 v150, v201
	s_waitcnt vmcnt(4)
	ds_write_b32 v152, v202
	s_waitcnt vmcnt(3)
	ds_write_b32 v154, v203
	s_waitcnt vmcnt(2)
	ds_write_b32 v156, v204
	s_waitcnt vmcnt(1)
	ds_write_b32 v158, v205
	s_waitcnt vmcnt(0)
	ds_write_b32 v160, v206
	s_and_b32 s4, 0xffff, s4
	s_lshl_b32 s4, s4, 1
	s_and_b32 s3, 0xffff, s3
	s_cmpk_gt_u32 s3, 0x57
	s_cselect_b32 s3, 0xfffff500, 0
	v_lshl_add_u64 v[66:67], v[26:27], 0, s[4:5]
	s_cselect_b32 s4, 0x80, 0
	s_add_i32 s12, s3, s2
	s_lshl_b32 s12, s12, 1
	v_mov_b32_e32 v3, s2
	s_waitcnt lgkmcnt(0)
	s_and_b32 s12, s12, 0xffffff00
	v_bitop3_b32 v4, v37, s16, v3 bitop3:0xc8
	ds_read2_b32 v[34:35], v40 offset0:33 offset1:41
	ds_read2_b32 v[52:53], v40 offset1:8
	ds_read2_b32 v[54:55], v40 offset0:66 offset1:74
	ds_read2_b32 v[56:57], v40 offset0:99 offset1:107
	ds_read2_b32 v[58:59], v40 offset0:132 offset1:140
	ds_read2_b32 v[60:61], v40 offset0:165 offset1:173
	ds_read2_b32 v[62:63], v40 offset0:198 offset1:206
	ds_read2_b32 v[64:65], v40 offset0:231 offset1:239
	v_or_b32_e32 v4, s12, v4
	v_or3_b32 v68, v4, v44, s4
	v_or_b32_e32 v4, s2, v41
	v_add_lshl_u32 v4, v4, s3, 1
	s_waitcnt lgkmcnt(6)
	v_cvt_pk_bf16_f32 v48, v52, v34
	v_ashrrev_i32_e32 v69, 31, v68
	v_and_b32_e32 v4, 0xffffff00, v4
	v_bitop3_b32 v34, v41, s16, v3 bitop3:0xc8
	v_lshlrev_b64 v[68:69], 11, v[68:69]
	v_or3_b32 v4, v34, v4, v44
	s_waitcnt lgkmcnt(4)
	v_cvt_pk_bf16_f32 v49, v54, v56
	s_waitcnt lgkmcnt(2)
	v_cvt_pk_bf16_f32 v50, v58, v60
	s_waitcnt lgkmcnt(0)
	v_cvt_pk_bf16_f32 v51, v62, v64
	v_lshl_add_u64 v[68:69], v[66:67], 0, v[68:69]
	v_or3_b32 v34, v4, s4, 4
	global_store_dwordx4 v[68:69], v[48:51], off
	v_or_b32_e32 v4, s2, v42
	v_add_lshl_u32 v4, v4, s3, 1
	v_cvt_pk_bf16_f32 v48, v53, v35
	v_ashrrev_i32_e32 v35, 31, v34
	v_lshlrev_b64 v[34:35], 11, v[34:35]
	v_cvt_pk_bf16_f32 v49, v55, v57
	v_cvt_pk_bf16_f32 v50, v59, v61
	v_cvt_pk_bf16_f32 v51, v63, v65
	v_lshl_add_u64 v[34:35], v[66:67], 0, v[34:35]
	ds_read2_b32 v[52:53], v40 offset0:16 offset1:24
	ds_read2_b32 v[54:55], v40 offset0:49 offset1:57
	ds_read2_b32 v[56:57], v40 offset0:82 offset1:90
	ds_read2_b32 v[58:59], v40 offset0:115 offset1:123
	ds_read2_b32 v[60:61], v40 offset0:148 offset1:156
	ds_read2_b32 v[62:63], v40 offset0:181 offset1:189
	ds_read2_b32 v[64:65], v40 offset0:214 offset1:222
	ds_read2_b32 v[68:69], v40 offset0:247 offset1:255
	global_store_dwordx4 v[34:35], v[48:51], off
	v_and_b32_e32 v4, 0xffffff00, v4
	v_bitop3_b32 v34, v42, s16, v3 bitop3:0xc8
	v_or3_b32 v4, v34, v4, v44
	v_or3_b32 v34, v4, s4, 8
	v_or_b32_e32 v4, s2, v43
	v_ashrrev_i32_e32 v35, 31, v34
	v_add_lshl_u32 v4, v4, s3, 1
	v_lshlrev_b64 v[34:35], 11, v[34:35]
	v_and_b32_e32 v4, 0xffffff00, v4
	v_bitop3_b32 v3, v43, s16, v3 bitop3:0xc8
	s_waitcnt lgkmcnt(6)
	v_cvt_pk_bf16_f32 v48, v52, v54
	s_waitcnt lgkmcnt(4)
	v_cvt_pk_bf16_f32 v49, v56, v58
	s_waitcnt lgkmcnt(2)
	v_cvt_pk_bf16_f32 v50, v60, v62
	s_waitcnt lgkmcnt(0)
	v_cvt_pk_bf16_f32 v51, v64, v68
	v_lshl_add_u64 v[34:35], v[66:67], 0, v[34:35]
	v_or3_b32 v3, v3, v4, v39
	global_store_dwordx4 v[34:35], v[48:51], off
	v_or3_b32 v34, v3, s4, 12
	v_ashrrev_i32_e32 v35, 31, v34
	v_lshlrev_b64 v[34:35], 11, v[34:35]
	v_cvt_pk_bf16_f32 v48, v53, v55
	v_cvt_pk_bf16_f32 v49, v57, v59
	v_cvt_pk_bf16_f32 v50, v61, v63
	v_cvt_pk_bf16_f32 v51, v65, v69
	v_lshl_add_u64 v[34:35], v[66:67], 0, v[34:35]
	global_store_dwordx4 v[34:35], v[48:51], off
	s_waitcnt lgkmcnt(0)

.LBB0_27:
	s_lshl_b32 s19, s12, 1
	s_lshl_b32 s20, s4, 1
	v_or_b32_e32 v4, s20, v36
	s_add_i32 s22, s19, 4
	s_add_i32 s23, s20, 4
	v_mov_b32_e32 v51, v5
	s_add_i32 s27, s20, 8
	v_lshlrev_b64 v[64:65], 12, v[4:5]
	v_or_b32_e32 v50, s22, v3
	v_or_b32_e32 v4, s23, v36
	v_mov_b32_e32 v49, v5
	v_or_b32_e32 v48, s19, v3
	s_add_i32 s29, s20, 12
	v_lshlrev_b64 v[50:51], 12, v[50:51]
	v_lshlrev_b64 v[66:67], 12, v[4:5]
	v_or_b32_e32 v4, s27, v36
	s_add_i32 s26, s19, 8
	s_add_i32 s28, s19, 12
	s_add_i32 s31, s20, 16
	v_lshlrev_b64 v[48:49], 12, v[48:49]
	v_lshl_add_u64 v[64:65], v[34:35], 0, v[64:65]
	v_lshl_add_u64 v[50:51], v[34:35], 0, v[50:51]
	v_lshlrev_b64 v[68:69], 12, v[4:5]
	v_or_b32_e32 v4, s29, v36
	v_mov_b32_e32 v53, v5
	v_mov_b32_e32 v55, v5
	s_add_i32 s35, s20, 20
	v_or_b32_e32 v52, s26, v3
	v_or_b32_e32 v54, s28, v3
	v_lshl_add_u64 v[48:49], v[34:35], 0, v[48:49]
	v_lshl_add_u64 v[66:67], v[34:35], 0, v[66:67]
	global_load_dword v47, v[64:65], off
	global_load_dword v80, v[48:49], off
	global_load_dword v81, v[66:67], off
	global_load_dword v82, v[50:51], off
	v_lshlrev_b64 v[50:51], 12, v[4:5]
	v_or_b32_e32 v4, s31, v36
	s_add_i32 s30, s19, 16
	s_add_i32 s34, s19, 20
	s_add_i32 s37, s20, 24
	v_lshlrev_b64 v[52:53], 12, v[52:53]
	v_lshlrev_b64 v[54:55], 12, v[54:55]
	v_lshl_add_u64 v[48:49], v[34:35], 0, v[68:69]
	v_lshl_add_u64 v[50:51], v[34:35], 0, v[50:51]
	v_lshlrev_b64 v[64:65], 12, v[4:5]
	v_or_b32_e32 v4, s35, v36
	v_mov_b32_e32 v57, v5
	v_mov_b32_e32 v59, v5
	s_add_i32 s36, s19, 24
	s_add_i32 s38, s19, 28
	s_add_i32 s39, s20, 28
	v_or_b32_e32 v56, s30, v3
	v_or_b32_e32 v58, s34, v3
	v_lshl_add_u64 v[52:53], v[34:35], 0, v[52:53]
	v_lshl_add_u64 v[54:55], v[34:35], 0, v[54:55]
	global_load_dword v83, v[48:49], off
	global_load_dword v84, v[52:53], off
	global_load_dword v85, v[50:51], off
	global_load_dword v86, v[54:55], off
	v_lshlrev_b64 v[50:51], 12, v[4:5]
	v_or_b32_e32 v4, s37, v36
	v_mov_b32_e32 v61, v5
	v_mov_b32_e32 v63, v5
	v_or_b32_e32 v60, s36, v3
	v_or_b32_e32 v62, s38, v3
	v_lshlrev_b64 v[56:57], 12, v[56:57]
	v_lshlrev_b64 v[58:59], 12, v[58:59]
	v_lshl_add_u64 v[48:49], v[34:35], 0, v[64:65]
	v_lshl_add_u64 v[50:51], v[34:35], 0, v[50:51]
	v_lshlrev_b64 v[52:53], 12, v[4:5]
	v_or_b32_e32 v4, s39, v36
	v_lshlrev_b64 v[60:61], 12, v[60:61]
	v_lshlrev_b64 v[62:63], 12, v[62:63]
	v_lshl_add_u64 v[56:57], v[34:35], 0, v[56:57]
	v_lshl_add_u64 v[58:59], v[34:35], 0, v[58:59]
	global_load_dword v87, v[48:49], off
	global_load_dword v88, v[56:57], off
	global_load_dword v89, v[50:51], off
	global_load_dword v90, v[58:59], off
	v_lshl_add_u64 v[48:49], v[34:35], 0, v[52:53]
	v_lshlrev_b64 v[50:51], 12, v[4:5]
	v_lshl_add_u64 v[60:61], v[34:35], 0, v[60:61]
	v_lshl_add_u64 v[62:63], v[34:35], 0, v[62:63]
	v_lshl_add_u64 v[50:51], v[34:35], 0, v[50:51]
	global_load_dword v4, v[48:49], off
	global_load_dword v91, v[60:61], off
	global_load_dword v92, v[50:51], off
	global_load_dword v93, v[62:63], off
	v_or_b32_e32 v50, s19, v1
	v_or_b32_e32 v48, s20, v2
	s_add_i32 s4, s4, 16
	s_add_i32 s12, s12, 16
	s_add_i32 s13, s13, -16
	v_mad_u64_u32 v[48:49], s[20:21], v48, s14, v[8:9]
	v_mad_u64_u32 v[50:51], s[20:21], v50, s14, v[8:9]
	v_or_b32_e32 v49, s22, v1
	v_or_b32_e32 v51, s23, v2
	v_or_b32_e32 v58, s26, v1
	v_or_b32_e32 v56, s27, v2
	v_or_b32_e32 v62, s28, v1
	v_or_b32_e32 v60, s29, v2
	v_or_b32_e32 v66, s30, v1
	v_or_b32_e32 v64, s31, v2
	v_or_b32_e32 v70, s34, v1
	v_or_b32_e32 v68, s35, v2
	v_or_b32_e32 v74, s36, v1
	v_or_b32_e32 v72, s37, v2
	v_or_b32_e32 v78, s38, v1
	v_or_b32_e32 v76, s39, v2
	s_cmp_lg_u32 s13, 0
	v_mad_u64_u32 v[52:53], s[20:21], v51, s14, v[8:9]
	v_mad_u64_u32 v[54:55], s[20:21], v49, s14, v[8:9]
	v_mad_u64_u32 v[56:57], s[20:21], v56, s14, v[8:9]
	v_mad_u64_u32 v[58:59], s[20:21], v58, s14, v[8:9]
	v_mad_u64_u32 v[60:61], s[20:21], v60, s14, v[8:9]
	v_mad_u64_u32 v[62:63], s[20:21], v62, s14, v[8:9]
	v_mad_u64_u32 v[64:65], s[20:21], v64, s14, v[8:9]
	v_mad_u64_u32 v[66:67], s[20:21], v66, s14, v[8:9]
	v_mad_u64_u32 v[68:69], s[20:21], v68, s14, v[8:9]
	v_mad_u64_u32 v[70:71], s[20:21], v70, s14, v[8:9]
	v_mad_u64_u32 v[72:73], s[20:21], v72, s14, v[8:9]
	v_mad_u64_u32 v[74:75], s[20:21], v74, s14, v[8:9]
	v_mad_u64_u32 v[76:77], s[20:21], v76, s14, v[8:9]
	v_mad_u64_u32 v[78:79], s[20:21], v78, s14, v[8:9]
	v_mov_b32_e32 v125, v5
	s_lshl_b32 s19, s12, 1
	s_lshl_b32 s20, s4, 1
	v_or_b32_e32 v124, s20, v36
	s_add_i32 s22, s19, 4
	s_add_i32 s23, s20, 4
	v_mov_b32_e32 v131, v125
	s_add_i32 s27, s20, 8
	v_lshlrev_b64 v[144:145], 12, v[124:125]
	v_or_b32_e32 v130, s22, v3
	v_or_b32_e32 v124, s23, v36
	v_mov_b32_e32 v129, v125
	v_or_b32_e32 v128, s19, v3
	s_add_i32 s29, s20, 12
	v_lshlrev_b64 v[130:131], 12, v[130:131]
	v_lshlrev_b64 v[146:147], 12, v[124:125]
	v_or_b32_e32 v124, s27, v36
	s_add_i32 s26, s19, 8
	s_add_i32 s28, s19, 12
	s_add_i32 s31, s20, 16
	v_lshlrev_b64 v[128:129], 12, v[128:129]
	v_lshl_add_u64 v[144:145], v[34:35], 0, v[144:145]
	v_lshl_add_u64 v[130:131], v[34:35], 0, v[130:131]
	v_lshlrev_b64 v[148:149], 12, v[124:125]
	v_or_b32_e32 v124, s29, v36
	v_mov_b32_e32 v133, v125
	v_mov_b32_e32 v135, v125
	s_add_i32 s35, s20, 20
	v_or_b32_e32 v132, s26, v3
	v_or_b32_e32 v134, s28, v3
	v_lshl_add_u64 v[128:129], v[34:35], 0, v[128:129]
	v_lshl_add_u64 v[146:147], v[34:35], 0, v[146:147]
	global_load_dword v127, v[144:145], off
	global_load_dword v160, v[128:129], off
	global_load_dword v161, v[146:147], off
	global_load_dword v178, v[130:131], off
	v_lshlrev_b64 v[130:131], 12, v[124:125]
	v_or_b32_e32 v124, s31, v36
	s_add_i32 s30, s19, 16
	s_add_i32 s34, s19, 20
	s_add_i32 s37, s20, 24
	v_lshlrev_b64 v[132:133], 12, v[132:133]
	v_lshlrev_b64 v[134:135], 12, v[134:135]
	v_lshl_add_u64 v[128:129], v[34:35], 0, v[148:149]
	v_lshl_add_u64 v[130:131], v[34:35], 0, v[130:131]
	v_lshlrev_b64 v[144:145], 12, v[124:125]
	v_or_b32_e32 v124, s35, v36
	v_mov_b32_e32 v137, v125
	v_mov_b32_e32 v139, v125
	s_add_i32 s36, s19, 24
	s_add_i32 s38, s19, 28
	s_add_i32 s39, s20, 28
	v_or_b32_e32 v136, s30, v3
	v_or_b32_e32 v138, s34, v3
	v_lshl_add_u64 v[132:133], v[34:35], 0, v[132:133]
	v_lshl_add_u64 v[134:135], v[34:35], 0, v[134:135]
	global_load_dword v179, v[128:129], off
	global_load_dword v180, v[132:133], off
	global_load_dword v181, v[130:131], off
	global_load_dword v182, v[134:135], off
	v_lshlrev_b64 v[130:131], 12, v[124:125]
	v_or_b32_e32 v124, s37, v36
	v_mov_b32_e32 v141, v125
	v_mov_b32_e32 v143, v125
	v_or_b32_e32 v140, s36, v3
	v_or_b32_e32 v142, s38, v3
	v_lshlrev_b64 v[136:137], 12, v[136:137]
	v_lshlrev_b64 v[138:139], 12, v[138:139]
	v_lshl_add_u64 v[128:129], v[34:35], 0, v[144:145]
	v_lshl_add_u64 v[130:131], v[34:35], 0, v[130:131]
	v_lshlrev_b64 v[132:133], 12, v[124:125]
	v_or_b32_e32 v124, s39, v36
	v_lshlrev_b64 v[140:141], 12, v[140:141]
	v_lshlrev_b64 v[142:143], 12, v[142:143]
	v_lshl_add_u64 v[136:137], v[34:35], 0, v[136:137]
	v_lshl_add_u64 v[138:139], v[34:35], 0, v[138:139]
	global_load_dword v183, v[128:129], off
	global_load_dword v184, v[136:137], off
	global_load_dword v185, v[130:131], off
	global_load_dword v186, v[138:139], off
	v_lshl_add_u64 v[128:129], v[34:35], 0, v[132:133]
	v_lshlrev_b64 v[130:131], 12, v[124:125]
	v_lshl_add_u64 v[140:141], v[34:35], 0, v[140:141]
	v_lshl_add_u64 v[142:143], v[34:35], 0, v[142:143]
	v_lshl_add_u64 v[130:131], v[34:35], 0, v[130:131]
	global_load_dword v124, v[128:129], off
	global_load_dword v187, v[140:141], off
	global_load_dword v188, v[130:131], off
	global_load_dword v189, v[142:143], off
	v_or_b32_e32 v130, s19, v1
	v_or_b32_e32 v128, s20, v2
	s_add_i32 s4, s4, 16
	s_add_i32 s12, s12, 16
	s_add_i32 s13, s13, -16
	v_mad_u64_u32 v[128:129], s[20:21], v128, s14, v[8:9]
	v_mad_u64_u32 v[130:131], s[20:21], v130, s14, v[8:9]
	v_or_b32_e32 v129, s22, v1
	v_or_b32_e32 v131, s23, v2
	v_or_b32_e32 v138, s26, v1
	v_or_b32_e32 v136, s27, v2
	v_or_b32_e32 v142, s28, v1
	v_or_b32_e32 v140, s29, v2
	v_or_b32_e32 v146, s30, v1
	v_or_b32_e32 v144, s31, v2
	v_or_b32_e32 v150, s34, v1
	v_or_b32_e32 v148, s35, v2
	v_or_b32_e32 v154, s36, v1
	v_or_b32_e32 v152, s37, v2
	v_or_b32_e32 v158, s38, v1
	v_or_b32_e32 v156, s39, v2
	s_cmp_lg_u32 s13, 0
	v_mad_u64_u32 v[132:133], s[20:21], v131, s14, v[8:9]
	v_mad_u64_u32 v[134:135], s[20:21], v129, s14, v[8:9]
	v_mad_u64_u32 v[136:137], s[20:21], v136, s14, v[8:9]
	v_mad_u64_u32 v[138:139], s[20:21], v138, s14, v[8:9]
	v_mad_u64_u32 v[140:141], s[20:21], v140, s14, v[8:9]
	v_mad_u64_u32 v[142:143], s[20:21], v142, s14, v[8:9]
	v_mad_u64_u32 v[144:145], s[20:21], v144, s14, v[8:9]
	v_mad_u64_u32 v[146:147], s[20:21], v146, s14, v[8:9]
	v_mad_u64_u32 v[148:149], s[20:21], v148, s14, v[8:9]
	v_mad_u64_u32 v[150:151], s[20:21], v150, s14, v[8:9]
	v_mad_u64_u32 v[152:153], s[20:21], v152, s14, v[8:9]
	v_mad_u64_u32 v[154:155], s[20:21], v154, s14, v[8:9]
	v_mad_u64_u32 v[156:157], s[20:21], v156, s14, v[8:9]
	v_mad_u64_u32 v[158:159], s[20:21], v158, s14, v[8:9]
	s_waitcnt vmcnt(31)
	ds_write_b32 v48, v47
	s_waitcnt vmcnt(30)
	ds_write_b32 v50, v80
	s_waitcnt vmcnt(29)
	ds_write_b32 v52, v81
	s_waitcnt vmcnt(28)
	ds_write_b32 v54, v82
	s_waitcnt vmcnt(27)
	ds_write_b32 v56, v83
	s_waitcnt vmcnt(26)
	ds_write_b32 v58, v84
	s_waitcnt vmcnt(25)
	ds_write_b32 v60, v85
	s_waitcnt vmcnt(24)
	ds_write_b32 v62, v86
	s_waitcnt vmcnt(23)
	ds_write_b32 v64, v87
	s_waitcnt vmcnt(22)
	ds_write_b32 v66, v88
	s_waitcnt vmcnt(21)
	ds_write_b32 v68, v89
	s_waitcnt vmcnt(20)
	ds_write_b32 v70, v90
	s_waitcnt vmcnt(19)
	ds_write_b32 v72, v4
	s_waitcnt vmcnt(18)
	ds_write_b32 v74, v91
	s_waitcnt vmcnt(17)
	ds_write_b32 v76, v92
	s_waitcnt vmcnt(16)
	ds_write_b32 v78, v93
	s_waitcnt vmcnt(15)
	ds_write_b32 v128, v127
	s_waitcnt vmcnt(14)
	ds_write_b32 v130, v160
	s_waitcnt vmcnt(13)
	ds_write_b32 v132, v161
	s_waitcnt vmcnt(12)
	ds_write_b32 v134, v178
	s_waitcnt vmcnt(11)
	ds_write_b32 v136, v179
	s_waitcnt vmcnt(10)
	ds_write_b32 v138, v180
	s_waitcnt vmcnt(9)
	ds_write_b32 v140, v181
	s_waitcnt vmcnt(8)
	ds_write_b32 v142, v182
	s_waitcnt vmcnt(7)
	ds_write_b32 v144, v183
	s_waitcnt vmcnt(6)
	ds_write_b32 v146, v184
	s_waitcnt vmcnt(5)
	ds_write_b32 v148, v185
	s_waitcnt vmcnt(4)
	ds_write_b32 v150, v186
	s_waitcnt vmcnt(3)
	ds_write_b32 v152, v124
	s_waitcnt vmcnt(2)
	ds_write_b32 v154, v187
	s_waitcnt vmcnt(1)
	ds_write_b32 v156, v188
	s_waitcnt vmcnt(0)
	ds_write_b32 v158, v189
	v_or_b32_e32 v4, s2, v37
	s_and_b32 s4, s2, 0x300
	s_and_b32 s12, s2, 0xe0
	v_lshlrev_b32_e32 v4, 2, v4
	s_lshl_b32 s2, s18, 4
	s_waitcnt lgkmcnt(0)
	v_or_b32_e32 v3, s4, v38
	v_and_b32_e32 v4, 0x90, v4
	s_and_b32 s2, s2, 0x60
	s_lshl_b32 s4, s3, 1
	ds_read2_b32 v[34:35], v40 offset0:33 offset1:41
	ds_read2_b32 v[52:53], v40 offset1:8
	ds_read2_b32 v[54:55], v40 offset0:66 offset1:74
	ds_read2_b32 v[56:57], v40 offset0:99 offset1:107
	ds_read2_b32 v[58:59], v40 offset0:132 offset1:140
	ds_read2_b32 v[60:61], v40 offset0:165 offset1:173
	ds_read2_b32 v[62:63], v40 offset0:198 offset1:206
	ds_read2_b32 v[64:65], v40 offset0:231 offset1:239
	v_or3_b32 v4, s2, v4, v3
	v_lshl_add_u64 v[66:67], v[28:29], 0, s[4:5]
	v_lshlrev_b32_e32 v4, 11, v4
	v_lshl_add_u64 v[68:69], v[66:67], 0, v[4:5]
	v_or_b32_e32 v4, s12, v41
	s_waitcnt lgkmcnt(6)
	v_cvt_pk_bf16_f32 v48, v52, v34
	v_lshlrev_b32_e32 v34, 2, v4
	v_lshrrev_b32_e32 v4, 1, v4
	v_and_b32_e32 v34, 0x90, v34
	v_and_b32_e32 v4, 0x64, v4
	s_waitcnt lgkmcnt(4)
	v_cvt_pk_bf16_f32 v49, v54, v56
	s_waitcnt lgkmcnt(2)
	v_cvt_pk_bf16_f32 v50, v58, v60
	s_waitcnt lgkmcnt(0)
	v_cvt_pk_bf16_f32 v51, v62, v64
	v_or3_b32 v4, v4, v34, v3
	global_store_dwordx4 v[68:69], v[48:51], off
	v_lshlrev_b32_e32 v4, 11, v4
	s_nop 0
	v_cvt_pk_bf16_f32 v48, v53, v35
	v_cvt_pk_bf16_f32 v49, v55, v57
	v_cvt_pk_bf16_f32 v50, v59, v61
	v_cvt_pk_bf16_f32 v51, v63, v65
	v_lshl_add_u64 v[34:35], v[66:67], 0, v[4:5]
	ds_read2_b32 v[52:53], v40 offset0:49 offset1:57
	ds_read2_b32 v[54:55], v40 offset0:16 offset1:24
	ds_read2_b32 v[56:57], v40 offset0:82 offset1:90
	ds_read2_b32 v[58:59], v40 offset0:115 offset1:123
	ds_read2_b32 v[60:61], v40 offset0:148 offset1:156
	ds_read2_b32 v[62:63], v40 offset0:181 offset1:189
	ds_read2_b32 v[64:65], v40 offset0:214 offset1:222
	ds_read2_b32 v[68:69], v40 offset0:247 offset1:255
	v_or_b32_e32 v4, s12, v42
	global_store_dwordx4 v[34:35], v[48:51], off
	v_lshlrev_b32_e32 v34, 2, v4
	v_lshrrev_b32_e32 v4, 1, v4
	v_and_b32_e32 v34, 0x90, v34
	v_and_b32_e32 v4, 0x68, v4
	v_or3_b32 v4, v4, v34, v3
	v_lshlrev_b32_e32 v4, 11, v4
	s_waitcnt lgkmcnt(6)
	v_cvt_pk_bf16_f32 v48, v54, v52
	s_waitcnt lgkmcnt(4)
	v_cvt_pk_bf16_f32 v49, v56, v58
	s_waitcnt lgkmcnt(2)
	v_cvt_pk_bf16_f32 v50, v60, v62
	s_waitcnt lgkmcnt(0)
	v_cvt_pk_bf16_f32 v51, v64, v68
	v_lshl_add_u64 v[34:35], v[66:67], 0, v[4:5]
	v_or_b32_e32 v4, s12, v43
	global_store_dwordx4 v[34:35], v[48:51], off
	v_lshlrev_b32_e32 v34, 2, v4
	v_lshrrev_b32_e32 v4, 1, v4
	v_and_b32_e32 v34, 0x90, v34
	v_and_b32_e32 v4, 0x6c, v4
	v_or3_b32 v3, v4, v34, v3
	v_lshlrev_b32_e32 v4, 11, v3
	v_cvt_pk_bf16_f32 v48, v55, v53
	v_cvt_pk_bf16_f32 v49, v57, v59
	v_cvt_pk_bf16_f32 v50, v61, v63
	v_cvt_pk_bf16_f32 v51, v65, v69
	v_lshl_add_u64 v[34:35], v[66:67], 0, v[4:5]
	global_store_dwordx4 v[34:35], v[48:51], off
	s_waitcnt lgkmcnt(0)

.LBB0_32:
	s_lshl_b32 s19, s12, 1
	s_lshl_b32 s20, s4, 1
	v_or_b32_e32 v4, s20, v36
	s_add_i32 s22, s19, 4
	s_add_i32 s23, s20, 4
	v_mov_b32_e32 v51, v5
	s_add_i32 s27, s20, 8
	v_lshlrev_b64 v[64:65], 12, v[4:5]
	v_or_b32_e32 v50, s22, v3
	v_or_b32_e32 v4, s23, v36
	v_mov_b32_e32 v49, v5
	v_or_b32_e32 v48, s19, v3
	s_add_i32 s29, s20, 12
	v_lshlrev_b64 v[50:51], 12, v[50:51]
	v_lshlrev_b64 v[66:67], 12, v[4:5]
	v_or_b32_e32 v4, s27, v36
	s_add_i32 s26, s19, 8
	s_add_i32 s28, s19, 12
	s_add_i32 s31, s20, 16
	v_lshlrev_b64 v[48:49], 12, v[48:49]
	v_lshl_add_u64 v[64:65], v[34:35], 0, v[64:65]
	v_lshl_add_u64 v[50:51], v[34:35], 0, v[50:51]
	v_lshlrev_b64 v[68:69], 12, v[4:5]
	v_or_b32_e32 v4, s29, v36
	v_mov_b32_e32 v53, v5
	v_mov_b32_e32 v55, v5
	s_add_i32 s35, s20, 20
	v_or_b32_e32 v52, s26, v3
	v_or_b32_e32 v54, s28, v3
	v_lshl_add_u64 v[48:49], v[34:35], 0, v[48:49]
	v_lshl_add_u64 v[66:67], v[34:35], 0, v[66:67]
	global_load_dword v47, v[64:65], off
	global_load_dword v80, v[48:49], off
	global_load_dword v81, v[66:67], off
	global_load_dword v82, v[50:51], off
	v_lshlrev_b64 v[50:51], 12, v[4:5]
	v_or_b32_e32 v4, s31, v36
	s_add_i32 s30, s19, 16
	s_add_i32 s34, s19, 20
	s_add_i32 s37, s20, 24
	v_lshlrev_b64 v[52:53], 12, v[52:53]
	v_lshlrev_b64 v[54:55], 12, v[54:55]
	v_lshl_add_u64 v[48:49], v[34:35], 0, v[68:69]
	v_lshl_add_u64 v[50:51], v[34:35], 0, v[50:51]
	v_lshlrev_b64 v[64:65], 12, v[4:5]
	v_or_b32_e32 v4, s35, v36
	v_mov_b32_e32 v57, v5
	v_mov_b32_e32 v59, v5
	s_add_i32 s36, s19, 24
	s_add_i32 s38, s19, 28
	s_add_i32 s39, s20, 28
	v_or_b32_e32 v56, s30, v3
	v_or_b32_e32 v58, s34, v3
	v_lshl_add_u64 v[52:53], v[34:35], 0, v[52:53]
	v_lshl_add_u64 v[54:55], v[34:35], 0, v[54:55]
	global_load_dword v83, v[48:49], off
	global_load_dword v84, v[52:53], off
	global_load_dword v85, v[50:51], off
	global_load_dword v86, v[54:55], off
	v_lshlrev_b64 v[50:51], 12, v[4:5]
	v_or_b32_e32 v4, s37, v36
	v_mov_b32_e32 v61, v5
	v_mov_b32_e32 v63, v5
	v_or_b32_e32 v60, s36, v3
	v_or_b32_e32 v62, s38, v3
	v_lshlrev_b64 v[56:57], 12, v[56:57]
	v_lshlrev_b64 v[58:59], 12, v[58:59]
	v_lshl_add_u64 v[48:49], v[34:35], 0, v[64:65]
	v_lshl_add_u64 v[50:51], v[34:35], 0, v[50:51]
	v_lshlrev_b64 v[52:53], 12, v[4:5]
	v_or_b32_e32 v4, s39, v36
	v_lshlrev_b64 v[60:61], 12, v[60:61]
	v_lshlrev_b64 v[62:63], 12, v[62:63]
	v_lshl_add_u64 v[56:57], v[34:35], 0, v[56:57]
	v_lshl_add_u64 v[58:59], v[34:35], 0, v[58:59]
	global_load_dword v87, v[48:49], off
	global_load_dword v88, v[56:57], off
	global_load_dword v89, v[50:51], off
	global_load_dword v90, v[58:59], off
	v_lshl_add_u64 v[48:49], v[34:35], 0, v[52:53]
	v_lshlrev_b64 v[50:51], 12, v[4:5]
	v_lshl_add_u64 v[60:61], v[34:35], 0, v[60:61]
	v_lshl_add_u64 v[62:63], v[34:35], 0, v[62:63]
	v_lshl_add_u64 v[50:51], v[34:35], 0, v[50:51]
	global_load_dword v4, v[48:49], off
	global_load_dword v91, v[60:61], off
	global_load_dword v92, v[50:51], off
	global_load_dword v93, v[62:63], off
	v_or_b32_e32 v50, s19, v1
	v_or_b32_e32 v48, s20, v2
	s_add_i32 s4, s4, 16
	s_add_i32 s12, s12, 16
	s_add_i32 s13, s13, -16
	v_mad_u64_u32 v[48:49], s[20:21], v48, s14, v[8:9]
	v_mad_u64_u32 v[50:51], s[20:21], v50, s14, v[8:9]
	v_or_b32_e32 v49, s22, v1
	v_or_b32_e32 v51, s23, v2
	v_or_b32_e32 v58, s26, v1
	v_or_b32_e32 v56, s27, v2
	v_or_b32_e32 v62, s28, v1
	v_or_b32_e32 v60, s29, v2
	v_or_b32_e32 v66, s30, v1
	v_or_b32_e32 v64, s31, v2
	v_or_b32_e32 v70, s34, v1
	v_or_b32_e32 v68, s35, v2
	v_or_b32_e32 v74, s36, v1
	v_or_b32_e32 v72, s37, v2
	v_or_b32_e32 v78, s38, v1
	v_or_b32_e32 v76, s39, v2
	s_cmp_lg_u32 s13, 0
	v_mad_u64_u32 v[52:53], s[20:21], v51, s14, v[8:9]
	v_mad_u64_u32 v[54:55], s[20:21], v49, s14, v[8:9]
	v_mad_u64_u32 v[56:57], s[20:21], v56, s14, v[8:9]
	v_mad_u64_u32 v[58:59], s[20:21], v58, s14, v[8:9]
	v_mad_u64_u32 v[60:61], s[20:21], v60, s14, v[8:9]
	v_mad_u64_u32 v[62:63], s[20:21], v62, s14, v[8:9]
	v_mad_u64_u32 v[64:65], s[20:21], v64, s14, v[8:9]
	v_mad_u64_u32 v[66:67], s[20:21], v66, s14, v[8:9]
	v_mad_u64_u32 v[68:69], s[20:21], v68, s14, v[8:9]
	v_mad_u64_u32 v[70:71], s[20:21], v70, s14, v[8:9]
	v_mad_u64_u32 v[72:73], s[20:21], v72, s14, v[8:9]
	v_mad_u64_u32 v[74:75], s[20:21], v74, s14, v[8:9]
	v_mad_u64_u32 v[76:77], s[20:21], v76, s14, v[8:9]
	v_mad_u64_u32 v[78:79], s[20:21], v78, s14, v[8:9]
	v_mov_b32_e32 v125, v5
	s_lshl_b32 s19, s12, 1
	s_lshl_b32 s20, s4, 1
	v_or_b32_e32 v124, s20, v36
	s_add_i32 s22, s19, 4
	s_add_i32 s23, s20, 4
	v_mov_b32_e32 v131, v125
	s_add_i32 s27, s20, 8
	v_lshlrev_b64 v[144:145], 12, v[124:125]
	v_or_b32_e32 v130, s22, v3
	v_or_b32_e32 v124, s23, v36
	v_mov_b32_e32 v129, v125
	v_or_b32_e32 v128, s19, v3
	s_add_i32 s29, s20, 12
	v_lshlrev_b64 v[130:131], 12, v[130:131]
	v_lshlrev_b64 v[146:147], 12, v[124:125]
	v_or_b32_e32 v124, s27, v36
	s_add_i32 s26, s19, 8
	s_add_i32 s28, s19, 12
	s_add_i32 s31, s20, 16
	v_lshlrev_b64 v[128:129], 12, v[128:129]
	v_lshl_add_u64 v[144:145], v[34:35], 0, v[144:145]
	v_lshl_add_u64 v[130:131], v[34:35], 0, v[130:131]
	v_lshlrev_b64 v[148:149], 12, v[124:125]
	v_or_b32_e32 v124, s29, v36
	v_mov_b32_e32 v133, v125
	v_mov_b32_e32 v135, v125
	s_add_i32 s35, s20, 20
	v_or_b32_e32 v132, s26, v3
	v_or_b32_e32 v134, s28, v3
	v_lshl_add_u64 v[128:129], v[34:35], 0, v[128:129]
	v_lshl_add_u64 v[146:147], v[34:35], 0, v[146:147]
	global_load_dword v127, v[144:145], off
	global_load_dword v160, v[128:129], off
	global_load_dword v161, v[146:147], off
	global_load_dword v178, v[130:131], off
	v_lshlrev_b64 v[130:131], 12, v[124:125]
	v_or_b32_e32 v124, s31, v36
	s_add_i32 s30, s19, 16
	s_add_i32 s34, s19, 20
	s_add_i32 s37, s20, 24
	v_lshlrev_b64 v[132:133], 12, v[132:133]
	v_lshlrev_b64 v[134:135], 12, v[134:135]
	v_lshl_add_u64 v[128:129], v[34:35], 0, v[148:149]
	v_lshl_add_u64 v[130:131], v[34:35], 0, v[130:131]
	v_lshlrev_b64 v[144:145], 12, v[124:125]
	v_or_b32_e32 v124, s35, v36
	v_mov_b32_e32 v137, v125
	v_mov_b32_e32 v139, v125
	s_add_i32 s36, s19, 24
	s_add_i32 s38, s19, 28
	s_add_i32 s39, s20, 28
	v_or_b32_e32 v136, s30, v3
	v_or_b32_e32 v138, s34, v3
	v_lshl_add_u64 v[132:133], v[34:35], 0, v[132:133]
	v_lshl_add_u64 v[134:135], v[34:35], 0, v[134:135]
	global_load_dword v179, v[128:129], off
	global_load_dword v180, v[132:133], off
	global_load_dword v181, v[130:131], off
	global_load_dword v182, v[134:135], off
	v_lshlrev_b64 v[130:131], 12, v[124:125]
	v_or_b32_e32 v124, s37, v36
	v_mov_b32_e32 v141, v125
	v_mov_b32_e32 v143, v125
	v_or_b32_e32 v140, s36, v3
	v_or_b32_e32 v142, s38, v3
	v_lshlrev_b64 v[136:137], 12, v[136:137]
	v_lshlrev_b64 v[138:139], 12, v[138:139]
	v_lshl_add_u64 v[128:129], v[34:35], 0, v[144:145]
	v_lshl_add_u64 v[130:131], v[34:35], 0, v[130:131]
	v_lshlrev_b64 v[132:133], 12, v[124:125]
	v_or_b32_e32 v124, s39, v36
	v_lshlrev_b64 v[140:141], 12, v[140:141]
	v_lshlrev_b64 v[142:143], 12, v[142:143]
	v_lshl_add_u64 v[136:137], v[34:35], 0, v[136:137]
	v_lshl_add_u64 v[138:139], v[34:35], 0, v[138:139]
	global_load_dword v183, v[128:129], off
	global_load_dword v184, v[136:137], off
	global_load_dword v185, v[130:131], off
	global_load_dword v186, v[138:139], off
	v_lshl_add_u64 v[128:129], v[34:35], 0, v[132:133]
	v_lshlrev_b64 v[130:131], 12, v[124:125]
	v_lshl_add_u64 v[140:141], v[34:35], 0, v[140:141]
	v_lshl_add_u64 v[142:143], v[34:35], 0, v[142:143]
	v_lshl_add_u64 v[130:131], v[34:35], 0, v[130:131]
	global_load_dword v124, v[128:129], off
	global_load_dword v187, v[140:141], off
	global_load_dword v188, v[130:131], off
	global_load_dword v189, v[142:143], off
	v_or_b32_e32 v130, s19, v1
	v_or_b32_e32 v128, s20, v2
	s_add_i32 s4, s4, 16
	s_add_i32 s12, s12, 16
	s_add_i32 s13, s13, -16
	v_mad_u64_u32 v[128:129], s[20:21], v128, s14, v[8:9]
	v_mad_u64_u32 v[130:131], s[20:21], v130, s14, v[8:9]
	v_or_b32_e32 v129, s22, v1
	v_or_b32_e32 v131, s23, v2
	v_or_b32_e32 v138, s26, v1
	v_or_b32_e32 v136, s27, v2
	v_or_b32_e32 v142, s28, v1
	v_or_b32_e32 v140, s29, v2
	v_or_b32_e32 v146, s30, v1
	v_or_b32_e32 v144, s31, v2
	v_or_b32_e32 v150, s34, v1
	v_or_b32_e32 v148, s35, v2
	v_or_b32_e32 v154, s36, v1
	v_or_b32_e32 v152, s37, v2
	v_or_b32_e32 v158, s38, v1
	v_or_b32_e32 v156, s39, v2
	s_cmp_lg_u32 s13, 0
	v_mad_u64_u32 v[132:133], s[20:21], v131, s14, v[8:9]
	v_mad_u64_u32 v[134:135], s[20:21], v129, s14, v[8:9]
	v_mad_u64_u32 v[136:137], s[20:21], v136, s14, v[8:9]
	v_mad_u64_u32 v[138:139], s[20:21], v138, s14, v[8:9]
	v_mad_u64_u32 v[140:141], s[20:21], v140, s14, v[8:9]
	v_mad_u64_u32 v[142:143], s[20:21], v142, s14, v[8:9]
	v_mad_u64_u32 v[144:145], s[20:21], v144, s14, v[8:9]
	v_mad_u64_u32 v[146:147], s[20:21], v146, s14, v[8:9]
	v_mad_u64_u32 v[148:149], s[20:21], v148, s14, v[8:9]
	v_mad_u64_u32 v[150:151], s[20:21], v150, s14, v[8:9]
	v_mad_u64_u32 v[152:153], s[20:21], v152, s14, v[8:9]
	v_mad_u64_u32 v[154:155], s[20:21], v154, s14, v[8:9]
	v_mad_u64_u32 v[156:157], s[20:21], v156, s14, v[8:9]
	v_mad_u64_u32 v[158:159], s[20:21], v158, s14, v[8:9]
	s_waitcnt vmcnt(31)
	ds_write_b32 v48, v47
	s_waitcnt vmcnt(30)
	ds_write_b32 v50, v80
	s_waitcnt vmcnt(29)
	ds_write_b32 v52, v81
	s_waitcnt vmcnt(28)
	ds_write_b32 v54, v82
	s_waitcnt vmcnt(27)
	ds_write_b32 v56, v83
	s_waitcnt vmcnt(26)
	ds_write_b32 v58, v84
	s_waitcnt vmcnt(25)
	ds_write_b32 v60, v85
	s_waitcnt vmcnt(24)
	ds_write_b32 v62, v86
	s_waitcnt vmcnt(23)
	ds_write_b32 v64, v87
	s_waitcnt vmcnt(22)
	ds_write_b32 v66, v88
	s_waitcnt vmcnt(21)
	ds_write_b32 v68, v89
	s_waitcnt vmcnt(20)
	ds_write_b32 v70, v90
	s_waitcnt vmcnt(19)
	ds_write_b32 v72, v4
	s_waitcnt vmcnt(18)
	ds_write_b32 v74, v91
	s_waitcnt vmcnt(17)
	ds_write_b32 v76, v92
	s_waitcnt vmcnt(16)
	ds_write_b32 v78, v93
	s_waitcnt vmcnt(15)
	ds_write_b32 v128, v127
	s_waitcnt vmcnt(14)
	ds_write_b32 v130, v160
	s_waitcnt vmcnt(13)
	ds_write_b32 v132, v161
	s_waitcnt vmcnt(12)
	ds_write_b32 v134, v178
	s_waitcnt vmcnt(11)
	ds_write_b32 v136, v179
	s_waitcnt vmcnt(10)
	ds_write_b32 v138, v180
	s_waitcnt vmcnt(9)
	ds_write_b32 v140, v181
	s_waitcnt vmcnt(8)
	ds_write_b32 v142, v182
	s_waitcnt vmcnt(7)
	ds_write_b32 v144, v183
	s_waitcnt vmcnt(6)
	ds_write_b32 v146, v184
	s_waitcnt vmcnt(5)
	ds_write_b32 v148, v185
	s_waitcnt vmcnt(4)
	ds_write_b32 v150, v186
	s_waitcnt vmcnt(3)
	ds_write_b32 v152, v124
	s_waitcnt vmcnt(2)
	ds_write_b32 v154, v187
	s_waitcnt vmcnt(1)
	ds_write_b32 v156, v188
	s_waitcnt vmcnt(0)
	ds_write_b32 v158, v189
	v_or_b32_e32 v4, s2, v37
	s_and_b32 s4, s2, 0x300
	s_and_b32 s12, s2, 0xe0
	v_lshlrev_b32_e32 v4, 2, v4
	s_lshl_b32 s2, s18, 4
	s_waitcnt lgkmcnt(0)
	v_or_b32_e32 v3, s4, v45
	v_and_b32_e32 v4, 0x90, v4
	s_and_b32 s2, s2, 0x60
	s_lshl_b32 s4, s3, 1
	ds_read2_b32 v[34:35], v40 offset0:33 offset1:41
	ds_read2_b32 v[52:53], v40 offset1:8
	ds_read2_b32 v[54:55], v40 offset0:66 offset1:74
	ds_read2_b32 v[56:57], v40 offset0:99 offset1:107
	ds_read2_b32 v[58:59], v40 offset0:132 offset1:140
	ds_read2_b32 v[60:61], v40 offset0:165 offset1:173
	ds_read2_b32 v[62:63], v40 offset0:198 offset1:206
	ds_read2_b32 v[64:65], v40 offset0:231 offset1:239
	v_or3_b32 v4, s2, v4, v3
	v_lshl_add_u64 v[66:67], v[30:31], 0, s[4:5]
	v_lshlrev_b32_e32 v4, 10, v4
	v_lshl_add_u64 v[68:69], v[66:67], 0, v[4:5]
	v_or_b32_e32 v4, s12, v41
	s_waitcnt lgkmcnt(6)
	v_cvt_pk_bf16_f32 v48, v52, v34
	v_lshlrev_b32_e32 v34, 2, v4
	v_lshrrev_b32_e32 v4, 1, v4
	v_and_b32_e32 v34, 0x90, v34
	v_and_b32_e32 v4, 0x64, v4
	s_waitcnt lgkmcnt(4)
	v_cvt_pk_bf16_f32 v49, v54, v56
	s_waitcnt lgkmcnt(2)
	v_cvt_pk_bf16_f32 v50, v58, v60
	s_waitcnt lgkmcnt(0)
	v_cvt_pk_bf16_f32 v51, v62, v64
	v_or3_b32 v4, v4, v34, v3
	global_store_dwordx4 v[68:69], v[48:51], off
	v_lshlrev_b32_e32 v4, 10, v4
	s_nop 0
	v_cvt_pk_bf16_f32 v48, v53, v35
	v_cvt_pk_bf16_f32 v49, v55, v57
	v_cvt_pk_bf16_f32 v50, v59, v61
	v_cvt_pk_bf16_f32 v51, v63, v65
	v_lshl_add_u64 v[34:35], v[66:67], 0, v[4:5]
	ds_read2_b32 v[52:53], v40 offset0:49 offset1:57
	ds_read2_b32 v[54:55], v40 offset0:16 offset1:24
	ds_read2_b32 v[56:57], v40 offset0:82 offset1:90
	ds_read2_b32 v[58:59], v40 offset0:115 offset1:123
	ds_read2_b32 v[60:61], v40 offset0:148 offset1:156
	ds_read2_b32 v[62:63], v40 offset0:181 offset1:189
	ds_read2_b32 v[64:65], v40 offset0:214 offset1:222
	ds_read2_b32 v[68:69], v40 offset0:247 offset1:255
	v_or_b32_e32 v4, s12, v42
	global_store_dwordx4 v[34:35], v[48:51], off
	v_lshlrev_b32_e32 v34, 2, v4
	v_lshrrev_b32_e32 v4, 1, v4
	v_and_b32_e32 v34, 0x90, v34
	v_and_b32_e32 v4, 0x68, v4
	v_or3_b32 v4, v4, v34, v3
	v_lshlrev_b32_e32 v4, 10, v4
	s_waitcnt lgkmcnt(6)
	v_cvt_pk_bf16_f32 v48, v54, v52
	s_waitcnt lgkmcnt(4)
	v_cvt_pk_bf16_f32 v49, v56, v58
	s_waitcnt lgkmcnt(2)
	v_cvt_pk_bf16_f32 v50, v60, v62
	s_waitcnt lgkmcnt(0)
	v_cvt_pk_bf16_f32 v51, v64, v68
	v_lshl_add_u64 v[34:35], v[66:67], 0, v[4:5]
	v_or_b32_e32 v4, s12, v43
	global_store_dwordx4 v[34:35], v[48:51], off
	v_lshlrev_b32_e32 v34, 2, v4
	v_lshrrev_b32_e32 v4, 1, v4
	v_and_b32_e32 v34, 0x90, v34
	v_and_b32_e32 v4, 0x6c, v4
	v_or3_b32 v3, v4, v34, v3
	v_lshlrev_b32_e32 v4, 10, v3
	v_cvt_pk_bf16_f32 v48, v55, v53
	v_cvt_pk_bf16_f32 v49, v57, v59
	v_cvt_pk_bf16_f32 v50, v61, v63
	v_cvt_pk_bf16_f32 v51, v65, v69
	v_lshl_add_u64 v[34:35], v[66:67], 0, v[4:5]
	global_store_dwordx4 v[34:35], v[48:51], off
	s_waitcnt lgkmcnt(0)

.LBB0_37:
	s_lshl_b32 s19, s12, 1
	s_lshl_b32 s20, s4, 1
	v_or_b32_e32 v4, s20, v36
	s_add_i32 s22, s19, 4
	s_add_i32 s23, s20, 4
	v_mov_b32_e32 v51, v5
	s_add_i32 s27, s20, 8
	v_lshlrev_b64 v[64:65], 12, v[4:5]
	v_or_b32_e32 v50, s22, v3
	v_or_b32_e32 v4, s23, v36
	v_mov_b32_e32 v49, v5
	v_or_b32_e32 v48, s19, v3
	s_add_i32 s29, s20, 12
	v_lshlrev_b64 v[50:51], 12, v[50:51]
	v_lshlrev_b64 v[66:67], 12, v[4:5]
	v_or_b32_e32 v4, s27, v36
	s_add_i32 s26, s19, 8
	s_add_i32 s28, s19, 12
	s_add_i32 s31, s20, 16
	v_lshlrev_b64 v[48:49], 12, v[48:49]
	v_lshl_add_u64 v[64:65], v[34:35], 0, v[64:65]
	v_lshl_add_u64 v[50:51], v[34:35], 0, v[50:51]
	v_lshlrev_b64 v[68:69], 12, v[4:5]
	v_or_b32_e32 v4, s29, v36
	v_mov_b32_e32 v53, v5
	v_mov_b32_e32 v55, v5
	s_add_i32 s35, s20, 20
	v_or_b32_e32 v52, s26, v3
	v_or_b32_e32 v54, s28, v3
	v_lshl_add_u64 v[48:49], v[34:35], 0, v[48:49]
	v_lshl_add_u64 v[66:67], v[34:35], 0, v[66:67]
	global_load_dword v47, v[64:65], off
	global_load_dword v80, v[48:49], off
	global_load_dword v81, v[66:67], off
	global_load_dword v82, v[50:51], off
	v_lshlrev_b64 v[50:51], 12, v[4:5]
	v_or_b32_e32 v4, s31, v36
	s_add_i32 s30, s19, 16
	s_add_i32 s34, s19, 20
	s_add_i32 s37, s20, 24
	v_lshlrev_b64 v[52:53], 12, v[52:53]
	v_lshlrev_b64 v[54:55], 12, v[54:55]
	v_lshl_add_u64 v[48:49], v[34:35], 0, v[68:69]
	v_lshl_add_u64 v[50:51], v[34:35], 0, v[50:51]
	v_lshlrev_b64 v[64:65], 12, v[4:5]
	v_or_b32_e32 v4, s35, v36
	v_mov_b32_e32 v57, v5
	v_mov_b32_e32 v59, v5
	s_add_i32 s36, s19, 24
	s_add_i32 s38, s19, 28
	s_add_i32 s39, s20, 28
	v_or_b32_e32 v56, s30, v3
	v_or_b32_e32 v58, s34, v3
	v_lshl_add_u64 v[52:53], v[34:35], 0, v[52:53]
	v_lshl_add_u64 v[54:55], v[34:35], 0, v[54:55]
	global_load_dword v83, v[48:49], off
	global_load_dword v84, v[52:53], off
	global_load_dword v85, v[50:51], off
	global_load_dword v86, v[54:55], off
	v_lshlrev_b64 v[50:51], 12, v[4:5]
	v_or_b32_e32 v4, s37, v36
	v_mov_b32_e32 v61, v5
	v_mov_b32_e32 v63, v5
	v_or_b32_e32 v60, s36, v3
	v_or_b32_e32 v62, s38, v3
	v_lshlrev_b64 v[56:57], 12, v[56:57]
	v_lshlrev_b64 v[58:59], 12, v[58:59]
	v_lshl_add_u64 v[48:49], v[34:35], 0, v[64:65]
	v_lshl_add_u64 v[50:51], v[34:35], 0, v[50:51]
	v_lshlrev_b64 v[52:53], 12, v[4:5]
	v_or_b32_e32 v4, s39, v36
	v_lshlrev_b64 v[60:61], 12, v[60:61]
	v_lshlrev_b64 v[62:63], 12, v[62:63]
	v_lshl_add_u64 v[56:57], v[34:35], 0, v[56:57]
	v_lshl_add_u64 v[58:59], v[34:35], 0, v[58:59]
	global_load_dword v87, v[48:49], off
	global_load_dword v88, v[56:57], off
	global_load_dword v89, v[50:51], off
	global_load_dword v90, v[58:59], off
	v_lshl_add_u64 v[48:49], v[34:35], 0, v[52:53]
	v_lshlrev_b64 v[50:51], 12, v[4:5]
	v_lshl_add_u64 v[60:61], v[34:35], 0, v[60:61]
	v_lshl_add_u64 v[62:63], v[34:35], 0, v[62:63]
	v_lshl_add_u64 v[50:51], v[34:35], 0, v[50:51]
	global_load_dword v4, v[48:49], off
	global_load_dword v91, v[60:61], off
	global_load_dword v92, v[50:51], off
	global_load_dword v93, v[62:63], off
	v_or_b32_e32 v50, s19, v1
	v_or_b32_e32 v48, s20, v2
	s_add_i32 s4, s4, 16
	s_add_i32 s12, s12, 16
	s_add_i32 s13, s13, -16
	v_mad_u64_u32 v[48:49], s[20:21], v48, s14, v[8:9]
	v_mad_u64_u32 v[50:51], s[20:21], v50, s14, v[8:9]
	v_or_b32_e32 v49, s22, v1
	v_or_b32_e32 v51, s23, v2
	v_or_b32_e32 v58, s26, v1
	v_or_b32_e32 v56, s27, v2
	v_or_b32_e32 v62, s28, v1
	v_or_b32_e32 v60, s29, v2
	v_or_b32_e32 v66, s30, v1
	v_or_b32_e32 v64, s31, v2
	v_or_b32_e32 v70, s34, v1
	v_or_b32_e32 v68, s35, v2
	v_or_b32_e32 v74, s36, v1
	v_or_b32_e32 v72, s37, v2
	v_or_b32_e32 v78, s38, v1
	v_or_b32_e32 v76, s39, v2
	s_cmp_lg_u32 s13, 0
	v_mad_u64_u32 v[52:53], s[20:21], v51, s14, v[8:9]
	v_mad_u64_u32 v[54:55], s[20:21], v49, s14, v[8:9]
	v_mad_u64_u32 v[56:57], s[20:21], v56, s14, v[8:9]
	v_mad_u64_u32 v[58:59], s[20:21], v58, s14, v[8:9]
	v_mad_u64_u32 v[60:61], s[20:21], v60, s14, v[8:9]
	v_mad_u64_u32 v[62:63], s[20:21], v62, s14, v[8:9]
	v_mad_u64_u32 v[64:65], s[20:21], v64, s14, v[8:9]
	v_mad_u64_u32 v[66:67], s[20:21], v66, s14, v[8:9]
	v_mad_u64_u32 v[68:69], s[20:21], v68, s14, v[8:9]
	v_mad_u64_u32 v[70:71], s[20:21], v70, s14, v[8:9]
	v_mad_u64_u32 v[72:73], s[20:21], v72, s14, v[8:9]
	v_mad_u64_u32 v[74:75], s[20:21], v74, s14, v[8:9]
	v_mad_u64_u32 v[76:77], s[20:21], v76, s14, v[8:9]
	v_mad_u64_u32 v[78:79], s[20:21], v78, s14, v[8:9]
	v_mov_b32_e32 v125, v5
	s_lshl_b32 s19, s12, 1
	s_lshl_b32 s20, s4, 1
	v_or_b32_e32 v124, s20, v36
	s_add_i32 s22, s19, 4
	s_add_i32 s23, s20, 4
	v_mov_b32_e32 v131, v125
	s_add_i32 s27, s20, 8
	v_lshlrev_b64 v[144:145], 12, v[124:125]
	v_or_b32_e32 v130, s22, v3
	v_or_b32_e32 v124, s23, v36
	v_mov_b32_e32 v129, v125
	v_or_b32_e32 v128, s19, v3
	s_add_i32 s29, s20, 12
	v_lshlrev_b64 v[130:131], 12, v[130:131]
	v_lshlrev_b64 v[146:147], 12, v[124:125]
	v_or_b32_e32 v124, s27, v36
	s_add_i32 s26, s19, 8
	s_add_i32 s28, s19, 12
	s_add_i32 s31, s20, 16
	v_lshlrev_b64 v[128:129], 12, v[128:129]
	v_lshl_add_u64 v[144:145], v[34:35], 0, v[144:145]
	v_lshl_add_u64 v[130:131], v[34:35], 0, v[130:131]
	v_lshlrev_b64 v[148:149], 12, v[124:125]
	v_or_b32_e32 v124, s29, v36
	v_mov_b32_e32 v133, v125
	v_mov_b32_e32 v135, v125
	s_add_i32 s35, s20, 20
	v_or_b32_e32 v132, s26, v3
	v_or_b32_e32 v134, s28, v3
	v_lshl_add_u64 v[128:129], v[34:35], 0, v[128:129]
	v_lshl_add_u64 v[146:147], v[34:35], 0, v[146:147]
	global_load_dword v127, v[144:145], off
	global_load_dword v160, v[128:129], off
	global_load_dword v161, v[146:147], off
	global_load_dword v178, v[130:131], off
	v_lshlrev_b64 v[130:131], 12, v[124:125]
	v_or_b32_e32 v124, s31, v36
	s_add_i32 s30, s19, 16
	s_add_i32 s34, s19, 20
	s_add_i32 s37, s20, 24
	v_lshlrev_b64 v[132:133], 12, v[132:133]
	v_lshlrev_b64 v[134:135], 12, v[134:135]
	v_lshl_add_u64 v[128:129], v[34:35], 0, v[148:149]
	v_lshl_add_u64 v[130:131], v[34:35], 0, v[130:131]
	v_lshlrev_b64 v[144:145], 12, v[124:125]
	v_or_b32_e32 v124, s35, v36
	v_mov_b32_e32 v137, v125
	v_mov_b32_e32 v139, v125
	s_add_i32 s36, s19, 24
	s_add_i32 s38, s19, 28
	s_add_i32 s39, s20, 28
	v_or_b32_e32 v136, s30, v3
	v_or_b32_e32 v138, s34, v3
	v_lshl_add_u64 v[132:133], v[34:35], 0, v[132:133]
	v_lshl_add_u64 v[134:135], v[34:35], 0, v[134:135]
	global_load_dword v179, v[128:129], off
	global_load_dword v180, v[132:133], off
	global_load_dword v181, v[130:131], off
	global_load_dword v182, v[134:135], off
	v_lshlrev_b64 v[130:131], 12, v[124:125]
	v_or_b32_e32 v124, s37, v36
	v_mov_b32_e32 v141, v125
	v_mov_b32_e32 v143, v125
	v_or_b32_e32 v140, s36, v3
	v_or_b32_e32 v142, s38, v3
	v_lshlrev_b64 v[136:137], 12, v[136:137]
	v_lshlrev_b64 v[138:139], 12, v[138:139]
	v_lshl_add_u64 v[128:129], v[34:35], 0, v[144:145]
	v_lshl_add_u64 v[130:131], v[34:35], 0, v[130:131]
	v_lshlrev_b64 v[132:133], 12, v[124:125]
	v_or_b32_e32 v124, s39, v36
	v_lshlrev_b64 v[140:141], 12, v[140:141]
	v_lshlrev_b64 v[142:143], 12, v[142:143]
	v_lshl_add_u64 v[136:137], v[34:35], 0, v[136:137]
	v_lshl_add_u64 v[138:139], v[34:35], 0, v[138:139]
	global_load_dword v183, v[128:129], off
	global_load_dword v184, v[136:137], off
	global_load_dword v185, v[130:131], off
	global_load_dword v186, v[138:139], off
	v_lshl_add_u64 v[128:129], v[34:35], 0, v[132:133]
	v_lshlrev_b64 v[130:131], 12, v[124:125]
	v_lshl_add_u64 v[140:141], v[34:35], 0, v[140:141]
	v_lshl_add_u64 v[142:143], v[34:35], 0, v[142:143]
	v_lshl_add_u64 v[130:131], v[34:35], 0, v[130:131]
	global_load_dword v124, v[128:129], off
	global_load_dword v187, v[140:141], off
	global_load_dword v188, v[130:131], off
	global_load_dword v189, v[142:143], off
	v_or_b32_e32 v130, s19, v1
	v_or_b32_e32 v128, s20, v2
	s_add_i32 s4, s4, 16
	s_add_i32 s12, s12, 16
	s_add_i32 s13, s13, -16
	v_mad_u64_u32 v[128:129], s[20:21], v128, s14, v[8:9]
	v_mad_u64_u32 v[130:131], s[20:21], v130, s14, v[8:9]
	v_or_b32_e32 v129, s22, v1
	v_or_b32_e32 v131, s23, v2
	v_or_b32_e32 v138, s26, v1
	v_or_b32_e32 v136, s27, v2
	v_or_b32_e32 v142, s28, v1
	v_or_b32_e32 v140, s29, v2
	v_or_b32_e32 v146, s30, v1
	v_or_b32_e32 v144, s31, v2
	v_or_b32_e32 v150, s34, v1
	v_or_b32_e32 v148, s35, v2
	v_or_b32_e32 v154, s36, v1
	v_or_b32_e32 v152, s37, v2
	v_or_b32_e32 v158, s38, v1
	v_or_b32_e32 v156, s39, v2
	s_cmp_lg_u32 s13, 0
	v_mad_u64_u32 v[132:133], s[20:21], v131, s14, v[8:9]
	v_mad_u64_u32 v[134:135], s[20:21], v129, s14, v[8:9]
	v_mad_u64_u32 v[136:137], s[20:21], v136, s14, v[8:9]
	v_mad_u64_u32 v[138:139], s[20:21], v138, s14, v[8:9]
	v_mad_u64_u32 v[140:141], s[20:21], v140, s14, v[8:9]
	v_mad_u64_u32 v[142:143], s[20:21], v142, s14, v[8:9]
	v_mad_u64_u32 v[144:145], s[20:21], v144, s14, v[8:9]
	v_mad_u64_u32 v[146:147], s[20:21], v146, s14, v[8:9]
	v_mad_u64_u32 v[148:149], s[20:21], v148, s14, v[8:9]
	v_mad_u64_u32 v[150:151], s[20:21], v150, s14, v[8:9]
	v_mad_u64_u32 v[152:153], s[20:21], v152, s14, v[8:9]
	v_mad_u64_u32 v[154:155], s[20:21], v154, s14, v[8:9]
	v_mad_u64_u32 v[156:157], s[20:21], v156, s14, v[8:9]
	v_mad_u64_u32 v[158:159], s[20:21], v158, s14, v[8:9]
	s_waitcnt vmcnt(31)
	ds_write_b32 v48, v47
	s_waitcnt vmcnt(30)
	ds_write_b32 v50, v80
	s_waitcnt vmcnt(29)
	ds_write_b32 v52, v81
	s_waitcnt vmcnt(28)
	ds_write_b32 v54, v82
	s_waitcnt vmcnt(27)
	ds_write_b32 v56, v83
	s_waitcnt vmcnt(26)
	ds_write_b32 v58, v84
	s_waitcnt vmcnt(25)
	ds_write_b32 v60, v85
	s_waitcnt vmcnt(24)
	ds_write_b32 v62, v86
	s_waitcnt vmcnt(23)
	ds_write_b32 v64, v87
	s_waitcnt vmcnt(22)
	ds_write_b32 v66, v88
	s_waitcnt vmcnt(21)
	ds_write_b32 v68, v89
	s_waitcnt vmcnt(20)
	ds_write_b32 v70, v90
	s_waitcnt vmcnt(19)
	ds_write_b32 v72, v4
	s_waitcnt vmcnt(18)
	ds_write_b32 v74, v91
	s_waitcnt vmcnt(17)
	ds_write_b32 v76, v92
	s_waitcnt vmcnt(16)
	ds_write_b32 v78, v93
	s_waitcnt vmcnt(15)
	ds_write_b32 v128, v127
	s_waitcnt vmcnt(14)
	ds_write_b32 v130, v160
	s_waitcnt vmcnt(13)
	ds_write_b32 v132, v161
	s_waitcnt vmcnt(12)
	ds_write_b32 v134, v178
	s_waitcnt vmcnt(11)
	ds_write_b32 v136, v179
	s_waitcnt vmcnt(10)
	ds_write_b32 v138, v180
	s_waitcnt vmcnt(9)
	ds_write_b32 v140, v181
	s_waitcnt vmcnt(8)
	ds_write_b32 v142, v182
	s_waitcnt vmcnt(7)
	ds_write_b32 v144, v183
	s_waitcnt vmcnt(6)
	ds_write_b32 v146, v184
	s_waitcnt vmcnt(5)
	ds_write_b32 v148, v185
	s_waitcnt vmcnt(4)
	ds_write_b32 v150, v186
	s_waitcnt vmcnt(3)
	ds_write_b32 v152, v124
	s_waitcnt vmcnt(2)
	ds_write_b32 v154, v187
	s_waitcnt vmcnt(1)
	ds_write_b32 v156, v188
	s_waitcnt vmcnt(0)
	ds_write_b32 v158, v189
	v_or_b32_e32 v4, s2, v37
	s_and_b32 s4, s2, 0x300
	s_and_b32 s12, s2, 0xe0
	v_lshlrev_b32_e32 v4, 2, v4
	s_lshl_b32 s2, s18, 4
	s_waitcnt lgkmcnt(0)
	v_or_b32_e32 v3, s4, v46
	v_and_b32_e32 v4, 0x90, v4
	s_and_b32 s2, s2, 0x60
	s_lshl_b32 s4, s3, 1
	ds_read2_b32 v[34:35], v40 offset0:33 offset1:41
	ds_read2_b32 v[52:53], v40 offset1:8
	ds_read2_b32 v[54:55], v40 offset0:66 offset1:74
	ds_read2_b32 v[56:57], v40 offset0:99 offset1:107
	ds_read2_b32 v[58:59], v40 offset0:132 offset1:140
	ds_read2_b32 v[60:61], v40 offset0:165 offset1:173
	ds_read2_b32 v[62:63], v40 offset0:198 offset1:206
	ds_read2_b32 v[64:65], v40 offset0:231 offset1:239
	v_or3_b32 v4, s2, v4, v3
	v_lshl_add_u64 v[66:67], v[30:31], 0, s[4:5]
	v_lshlrev_b32_e32 v4, 10, v4
	v_lshl_add_u64 v[68:69], v[66:67], 0, v[4:5]
	v_or_b32_e32 v4, s12, v41
	s_waitcnt lgkmcnt(6)
	v_cvt_pk_bf16_f32 v48, v52, v34
	v_lshlrev_b32_e32 v34, 2, v4
	v_lshrrev_b32_e32 v4, 1, v4
	v_and_b32_e32 v34, 0x90, v34
	v_and_b32_e32 v4, 0x64, v4
	s_waitcnt lgkmcnt(4)
	v_cvt_pk_bf16_f32 v49, v54, v56
	s_waitcnt lgkmcnt(2)
	v_cvt_pk_bf16_f32 v50, v58, v60
	s_waitcnt lgkmcnt(0)
	v_cvt_pk_bf16_f32 v51, v62, v64
	v_or3_b32 v4, v4, v34, v3
	global_store_dwordx4 v[68:69], v[48:51], off
	v_lshlrev_b32_e32 v4, 10, v4
	s_nop 0
	v_cvt_pk_bf16_f32 v48, v53, v35
	v_cvt_pk_bf16_f32 v49, v55, v57
	v_cvt_pk_bf16_f32 v50, v59, v61
	v_cvt_pk_bf16_f32 v51, v63, v65
	v_lshl_add_u64 v[34:35], v[66:67], 0, v[4:5]
	ds_read2_b32 v[52:53], v40 offset0:49 offset1:57
	ds_read2_b32 v[54:55], v40 offset0:16 offset1:24
	ds_read2_b32 v[56:57], v40 offset0:82 offset1:90
	ds_read2_b32 v[58:59], v40 offset0:115 offset1:123
	ds_read2_b32 v[60:61], v40 offset0:148 offset1:156
	ds_read2_b32 v[62:63], v40 offset0:181 offset1:189
	ds_read2_b32 v[64:65], v40 offset0:214 offset1:222
	ds_read2_b32 v[68:69], v40 offset0:247 offset1:255
	v_or_b32_e32 v4, s12, v42
	global_store_dwordx4 v[34:35], v[48:51], off
	v_lshlrev_b32_e32 v34, 2, v4
	v_lshrrev_b32_e32 v4, 1, v4
	v_and_b32_e32 v34, 0x90, v34
	v_and_b32_e32 v4, 0x68, v4
	v_or3_b32 v4, v4, v34, v3
	v_lshlrev_b32_e32 v4, 10, v4
	s_waitcnt lgkmcnt(6)
	v_cvt_pk_bf16_f32 v48, v54, v52
	s_waitcnt lgkmcnt(4)
	v_cvt_pk_bf16_f32 v49, v56, v58
	s_waitcnt lgkmcnt(2)
	v_cvt_pk_bf16_f32 v50, v60, v62
	s_waitcnt lgkmcnt(0)
	v_cvt_pk_bf16_f32 v51, v64, v68
	v_lshl_add_u64 v[34:35], v[66:67], 0, v[4:5]
	v_or_b32_e32 v4, s12, v43
	global_store_dwordx4 v[34:35], v[48:51], off
	v_lshlrev_b32_e32 v34, 2, v4
	v_lshrrev_b32_e32 v4, 1, v4
	v_and_b32_e32 v34, 0x90, v34
	v_and_b32_e32 v4, 0x6c, v4
	v_or3_b32 v3, v4, v34, v3
	v_lshlrev_b32_e32 v4, 10, v3
	v_cvt_pk_bf16_f32 v48, v55, v53
	v_cvt_pk_bf16_f32 v49, v57, v59
	v_cvt_pk_bf16_f32 v50, v61, v63
	v_cvt_pk_bf16_f32 v51, v65, v69
	v_lshl_add_u64 v[34:35], v[66:67], 0, v[4:5]
	global_store_dwordx4 v[34:35], v[48:51], off
	s_waitcnt lgkmcnt(0)

.LBB0_42:
	s_lshl_b32 s19, s12, 1
	s_lshl_b32 s20, s4, 1
	v_or_b32_e32 v4, s20, v36
	s_add_i32 s22, s19, 4
	s_add_i32 s23, s20, 4
	v_mov_b32_e32 v51, v5
	s_add_i32 s27, s20, 8
	v_lshlrev_b64 v[64:65], 12, v[4:5]
	v_or_b32_e32 v50, s22, v3
	v_or_b32_e32 v4, s23, v36
	v_mov_b32_e32 v49, v5
	v_or_b32_e32 v48, s19, v3
	s_add_i32 s29, s20, 12
	v_lshlrev_b64 v[50:51], 12, v[50:51]
	v_lshlrev_b64 v[66:67], 12, v[4:5]
	v_or_b32_e32 v4, s27, v36
	s_add_i32 s26, s19, 8
	s_add_i32 s28, s19, 12
	s_add_i32 s31, s20, 16
	v_lshlrev_b64 v[48:49], 12, v[48:49]
	v_lshl_add_u64 v[64:65], v[34:35], 0, v[64:65]
	v_lshl_add_u64 v[50:51], v[34:35], 0, v[50:51]
	v_lshlrev_b64 v[68:69], 12, v[4:5]
	v_or_b32_e32 v4, s29, v36
	v_mov_b32_e32 v53, v5
	v_mov_b32_e32 v55, v5
	s_add_i32 s35, s20, 20
	v_or_b32_e32 v52, s26, v3
	v_or_b32_e32 v54, s28, v3
	v_lshl_add_u64 v[48:49], v[34:35], 0, v[48:49]
	v_lshl_add_u64 v[66:67], v[34:35], 0, v[66:67]
	global_load_dword v47, v[64:65], off
	global_load_dword v80, v[48:49], off
	global_load_dword v81, v[66:67], off
	global_load_dword v82, v[50:51], off
	v_lshlrev_b64 v[50:51], 12, v[4:5]
	v_or_b32_e32 v4, s31, v36
	s_add_i32 s30, s19, 16
	s_add_i32 s34, s19, 20
	s_add_i32 s37, s20, 24
	v_lshlrev_b64 v[52:53], 12, v[52:53]
	v_lshlrev_b64 v[54:55], 12, v[54:55]
	v_lshl_add_u64 v[48:49], v[34:35], 0, v[68:69]
	v_lshl_add_u64 v[50:51], v[34:35], 0, v[50:51]
	v_lshlrev_b64 v[64:65], 12, v[4:5]
	v_or_b32_e32 v4, s35, v36
	v_mov_b32_e32 v57, v5
	v_mov_b32_e32 v59, v5
	s_add_i32 s36, s19, 24
	s_add_i32 s38, s19, 28
	s_add_i32 s39, s20, 28
	v_or_b32_e32 v56, s30, v3
	v_or_b32_e32 v58, s34, v3
	v_lshl_add_u64 v[52:53], v[34:35], 0, v[52:53]
	v_lshl_add_u64 v[54:55], v[34:35], 0, v[54:55]
	global_load_dword v83, v[48:49], off
	global_load_dword v84, v[52:53], off
	global_load_dword v85, v[50:51], off
	global_load_dword v86, v[54:55], off
	v_lshlrev_b64 v[50:51], 12, v[4:5]
	v_or_b32_e32 v4, s37, v36
	v_mov_b32_e32 v61, v5
	v_mov_b32_e32 v63, v5
	v_or_b32_e32 v60, s36, v3
	v_or_b32_e32 v62, s38, v3
	v_lshlrev_b64 v[56:57], 12, v[56:57]
	v_lshlrev_b64 v[58:59], 12, v[58:59]
	v_lshl_add_u64 v[48:49], v[34:35], 0, v[64:65]
	v_lshl_add_u64 v[50:51], v[34:35], 0, v[50:51]
	v_lshlrev_b64 v[52:53], 12, v[4:5]
	v_or_b32_e32 v4, s39, v36
	v_lshlrev_b64 v[60:61], 12, v[60:61]
	v_lshlrev_b64 v[62:63], 12, v[62:63]
	v_lshl_add_u64 v[56:57], v[34:35], 0, v[56:57]
	v_lshl_add_u64 v[58:59], v[34:35], 0, v[58:59]
	global_load_dword v87, v[48:49], off
	global_load_dword v88, v[56:57], off
	global_load_dword v89, v[50:51], off
	global_load_dword v90, v[58:59], off
	v_lshl_add_u64 v[48:49], v[34:35], 0, v[52:53]
	v_lshlrev_b64 v[50:51], 12, v[4:5]
	v_lshl_add_u64 v[60:61], v[34:35], 0, v[60:61]
	v_lshl_add_u64 v[62:63], v[34:35], 0, v[62:63]
	v_lshl_add_u64 v[50:51], v[34:35], 0, v[50:51]
	global_load_dword v4, v[48:49], off
	global_load_dword v91, v[60:61], off
	global_load_dword v92, v[50:51], off
	global_load_dword v93, v[62:63], off
	v_or_b32_e32 v50, s19, v1
	v_or_b32_e32 v48, s20, v2
	s_add_i32 s4, s4, 16
	s_add_i32 s12, s12, 16
	s_add_i32 s13, s13, -16
	v_mad_u64_u32 v[48:49], s[20:21], v48, s14, v[8:9]
	v_mad_u64_u32 v[50:51], s[20:21], v50, s14, v[8:9]
	v_or_b32_e32 v49, s22, v1
	v_or_b32_e32 v51, s23, v2
	v_or_b32_e32 v58, s26, v1
	v_or_b32_e32 v56, s27, v2
	v_or_b32_e32 v62, s28, v1
	v_or_b32_e32 v60, s29, v2
	v_or_b32_e32 v66, s30, v1
	v_or_b32_e32 v64, s31, v2
	v_or_b32_e32 v70, s34, v1
	v_or_b32_e32 v68, s35, v2
	v_or_b32_e32 v74, s36, v1
	v_or_b32_e32 v72, s37, v2
	v_or_b32_e32 v78, s38, v1
	v_or_b32_e32 v76, s39, v2
	s_cmp_lg_u32 s13, 0
	v_mad_u64_u32 v[52:53], s[20:21], v51, s14, v[8:9]
	v_mad_u64_u32 v[54:55], s[20:21], v49, s14, v[8:9]
	v_mad_u64_u32 v[56:57], s[20:21], v56, s14, v[8:9]
	v_mad_u64_u32 v[58:59], s[20:21], v58, s14, v[8:9]
	v_mad_u64_u32 v[60:61], s[20:21], v60, s14, v[8:9]
	v_mad_u64_u32 v[62:63], s[20:21], v62, s14, v[8:9]
	v_mad_u64_u32 v[64:65], s[20:21], v64, s14, v[8:9]
	v_mad_u64_u32 v[66:67], s[20:21], v66, s14, v[8:9]
	v_mad_u64_u32 v[68:69], s[20:21], v68, s14, v[8:9]
	v_mad_u64_u32 v[70:71], s[20:21], v70, s14, v[8:9]
	v_mad_u64_u32 v[72:73], s[20:21], v72, s14, v[8:9]
	v_mad_u64_u32 v[74:75], s[20:21], v74, s14, v[8:9]
	v_mad_u64_u32 v[76:77], s[20:21], v76, s14, v[8:9]
	v_mad_u64_u32 v[78:79], s[20:21], v78, s14, v[8:9]
	v_mov_b32_e32 v125, v5
	s_lshl_b32 s19, s12, 1
	s_lshl_b32 s20, s4, 1
	v_or_b32_e32 v124, s20, v36
	s_add_i32 s22, s19, 4
	s_add_i32 s23, s20, 4
	v_mov_b32_e32 v131, v125
	s_add_i32 s27, s20, 8
	v_lshlrev_b64 v[144:145], 12, v[124:125]
	v_or_b32_e32 v130, s22, v3
	v_or_b32_e32 v124, s23, v36
	v_mov_b32_e32 v129, v125
	v_or_b32_e32 v128, s19, v3
	s_add_i32 s29, s20, 12
	v_lshlrev_b64 v[130:131], 12, v[130:131]
	v_lshlrev_b64 v[146:147], 12, v[124:125]
	v_or_b32_e32 v124, s27, v36
	s_add_i32 s26, s19, 8
	s_add_i32 s28, s19, 12
	s_add_i32 s31, s20, 16
	v_lshlrev_b64 v[128:129], 12, v[128:129]
	v_lshl_add_u64 v[144:145], v[34:35], 0, v[144:145]
	v_lshl_add_u64 v[130:131], v[34:35], 0, v[130:131]
	v_lshlrev_b64 v[148:149], 12, v[124:125]
	v_or_b32_e32 v124, s29, v36
	v_mov_b32_e32 v133, v125
	v_mov_b32_e32 v135, v125
	s_add_i32 s35, s20, 20
	v_or_b32_e32 v132, s26, v3
	v_or_b32_e32 v134, s28, v3
	v_lshl_add_u64 v[128:129], v[34:35], 0, v[128:129]
	v_lshl_add_u64 v[146:147], v[34:35], 0, v[146:147]
	global_load_dword v127, v[144:145], off
	global_load_dword v160, v[128:129], off
	global_load_dword v161, v[146:147], off
	global_load_dword v178, v[130:131], off
	v_lshlrev_b64 v[130:131], 12, v[124:125]
	v_or_b32_e32 v124, s31, v36
	s_add_i32 s30, s19, 16
	s_add_i32 s34, s19, 20
	s_add_i32 s37, s20, 24
	v_lshlrev_b64 v[132:133], 12, v[132:133]
	v_lshlrev_b64 v[134:135], 12, v[134:135]
	v_lshl_add_u64 v[128:129], v[34:35], 0, v[148:149]
	v_lshl_add_u64 v[130:131], v[34:35], 0, v[130:131]
	v_lshlrev_b64 v[144:145], 12, v[124:125]
	v_or_b32_e32 v124, s35, v36
	v_mov_b32_e32 v137, v125
	v_mov_b32_e32 v139, v125
	s_add_i32 s36, s19, 24
	s_add_i32 s38, s19, 28
	s_add_i32 s39, s20, 28
	v_or_b32_e32 v136, s30, v3
	v_or_b32_e32 v138, s34, v3
	v_lshl_add_u64 v[132:133], v[34:35], 0, v[132:133]
	v_lshl_add_u64 v[134:135], v[34:35], 0, v[134:135]
	global_load_dword v179, v[128:129], off
	global_load_dword v180, v[132:133], off
	global_load_dword v181, v[130:131], off
	global_load_dword v182, v[134:135], off
	v_lshlrev_b64 v[130:131], 12, v[124:125]
	v_or_b32_e32 v124, s37, v36
	v_mov_b32_e32 v141, v125
	v_mov_b32_e32 v143, v125
	v_or_b32_e32 v140, s36, v3
	v_or_b32_e32 v142, s38, v3
	v_lshlrev_b64 v[136:137], 12, v[136:137]
	v_lshlrev_b64 v[138:139], 12, v[138:139]
	v_lshl_add_u64 v[128:129], v[34:35], 0, v[144:145]
	v_lshl_add_u64 v[130:131], v[34:35], 0, v[130:131]
	v_lshlrev_b64 v[132:133], 12, v[124:125]
	v_or_b32_e32 v124, s39, v36
	v_lshlrev_b64 v[140:141], 12, v[140:141]
	v_lshlrev_b64 v[142:143], 12, v[142:143]
	v_lshl_add_u64 v[136:137], v[34:35], 0, v[136:137]
	v_lshl_add_u64 v[138:139], v[34:35], 0, v[138:139]
	global_load_dword v183, v[128:129], off
	global_load_dword v184, v[136:137], off
	global_load_dword v185, v[130:131], off
	global_load_dword v186, v[138:139], off
	v_lshl_add_u64 v[128:129], v[34:35], 0, v[132:133]
	v_lshlrev_b64 v[130:131], 12, v[124:125]
	v_lshl_add_u64 v[140:141], v[34:35], 0, v[140:141]
	v_lshl_add_u64 v[142:143], v[34:35], 0, v[142:143]
	v_lshl_add_u64 v[130:131], v[34:35], 0, v[130:131]
	global_load_dword v124, v[128:129], off
	global_load_dword v187, v[140:141], off
	global_load_dword v188, v[130:131], off
	global_load_dword v189, v[142:143], off
	v_or_b32_e32 v130, s19, v1
	v_or_b32_e32 v128, s20, v2
	s_add_i32 s4, s4, 16
	s_add_i32 s12, s12, 16
	s_add_i32 s13, s13, -16
	v_mad_u64_u32 v[128:129], s[20:21], v128, s14, v[8:9]
	v_mad_u64_u32 v[130:131], s[20:21], v130, s14, v[8:9]
	v_or_b32_e32 v129, s22, v1
	v_or_b32_e32 v131, s23, v2
	v_or_b32_e32 v138, s26, v1
	v_or_b32_e32 v136, s27, v2
	v_or_b32_e32 v142, s28, v1
	v_or_b32_e32 v140, s29, v2
	v_or_b32_e32 v146, s30, v1
	v_or_b32_e32 v144, s31, v2
	v_or_b32_e32 v150, s34, v1
	v_or_b32_e32 v148, s35, v2
	v_or_b32_e32 v154, s36, v1
	v_or_b32_e32 v152, s37, v2
	v_or_b32_e32 v158, s38, v1
	v_or_b32_e32 v156, s39, v2
	s_cmp_lg_u32 s13, 0
	v_mad_u64_u32 v[132:133], s[20:21], v131, s14, v[8:9]
	v_mad_u64_u32 v[134:135], s[20:21], v129, s14, v[8:9]
	v_mad_u64_u32 v[136:137], s[20:21], v136, s14, v[8:9]
	v_mad_u64_u32 v[138:139], s[20:21], v138, s14, v[8:9]
	v_mad_u64_u32 v[140:141], s[20:21], v140, s14, v[8:9]
	v_mad_u64_u32 v[142:143], s[20:21], v142, s14, v[8:9]
	v_mad_u64_u32 v[144:145], s[20:21], v144, s14, v[8:9]
	v_mad_u64_u32 v[146:147], s[20:21], v146, s14, v[8:9]
	v_mad_u64_u32 v[148:149], s[20:21], v148, s14, v[8:9]
	v_mad_u64_u32 v[150:151], s[20:21], v150, s14, v[8:9]
	v_mad_u64_u32 v[152:153], s[20:21], v152, s14, v[8:9]
	v_mad_u64_u32 v[154:155], s[20:21], v154, s14, v[8:9]
	v_mad_u64_u32 v[156:157], s[20:21], v156, s14, v[8:9]
	v_mad_u64_u32 v[158:159], s[20:21], v158, s14, v[8:9]
	s_waitcnt vmcnt(31)
	ds_write_b32 v48, v47
	s_waitcnt vmcnt(30)
	ds_write_b32 v50, v80
	s_waitcnt vmcnt(29)
	ds_write_b32 v52, v81
	s_waitcnt vmcnt(28)
	ds_write_b32 v54, v82
	s_waitcnt vmcnt(27)
	ds_write_b32 v56, v83
	s_waitcnt vmcnt(26)
	ds_write_b32 v58, v84
	s_waitcnt vmcnt(25)
	ds_write_b32 v60, v85
	s_waitcnt vmcnt(24)
	ds_write_b32 v62, v86
	s_waitcnt vmcnt(23)
	ds_write_b32 v64, v87
	s_waitcnt vmcnt(22)
	ds_write_b32 v66, v88
	s_waitcnt vmcnt(21)
	ds_write_b32 v68, v89
	s_waitcnt vmcnt(20)
	ds_write_b32 v70, v90
	s_waitcnt vmcnt(19)
	ds_write_b32 v72, v4
	s_waitcnt vmcnt(18)
	ds_write_b32 v74, v91
	s_waitcnt vmcnt(17)
	ds_write_b32 v76, v92
	s_waitcnt vmcnt(16)
	ds_write_b32 v78, v93
	s_waitcnt vmcnt(15)
	ds_write_b32 v128, v127
	s_waitcnt vmcnt(14)
	ds_write_b32 v130, v160
	s_waitcnt vmcnt(13)
	ds_write_b32 v132, v161
	s_waitcnt vmcnt(12)
	ds_write_b32 v134, v178
	s_waitcnt vmcnt(11)
	ds_write_b32 v136, v179
	s_waitcnt vmcnt(10)
	ds_write_b32 v138, v180
	s_waitcnt vmcnt(9)
	ds_write_b32 v140, v181
	s_waitcnt vmcnt(8)
	ds_write_b32 v142, v182
	s_waitcnt vmcnt(7)
	ds_write_b32 v144, v183
	s_waitcnt vmcnt(6)
	ds_write_b32 v146, v184
	s_waitcnt vmcnt(5)
	ds_write_b32 v148, v185
	s_waitcnt vmcnt(4)
	ds_write_b32 v150, v186
	s_waitcnt vmcnt(3)
	ds_write_b32 v152, v124
	s_waitcnt vmcnt(2)
	ds_write_b32 v154, v187
	s_waitcnt vmcnt(1)
	ds_write_b32 v156, v188
	s_waitcnt vmcnt(0)
	ds_write_b32 v158, v189
	v_or_b32_e32 v4, s2, v37
	s_and_b32 s4, s2, 0x300
	s_and_b32 s12, s2, 0xe0
	v_lshlrev_b32_e32 v4, 2, v4
	s_lshl_b32 s2, s18, 4
	s_waitcnt lgkmcnt(0)
	v_or_b32_e32 v3, s4, v38
	v_and_b32_e32 v4, 0x90, v4
	s_and_b32 s2, s2, 0x60
	s_lshl_b32 s4, s3, 1
	ds_read2_b32 v[34:35], v40 offset0:33 offset1:41
	ds_read2_b32 v[52:53], v40 offset1:8
	ds_read2_b32 v[54:55], v40 offset0:66 offset1:74
	ds_read2_b32 v[56:57], v40 offset0:99 offset1:107
	ds_read2_b32 v[58:59], v40 offset0:132 offset1:140
	ds_read2_b32 v[60:61], v40 offset0:165 offset1:173
	ds_read2_b32 v[62:63], v40 offset0:198 offset1:206
	ds_read2_b32 v[64:65], v40 offset0:231 offset1:239
	v_or3_b32 v4, s2, v4, v3
	v_lshl_add_u64 v[66:67], v[30:31], 0, s[4:5]
	v_lshlrev_b32_e32 v4, 10, v4
	v_lshl_add_u64 v[68:69], v[66:67], 0, v[4:5]
	v_or_b32_e32 v4, s12, v41
	s_waitcnt lgkmcnt(6)
	v_cvt_pk_bf16_f32 v48, v52, v34
	v_lshlrev_b32_e32 v34, 2, v4
	v_lshrrev_b32_e32 v4, 1, v4
	v_and_b32_e32 v34, 0x90, v34
	v_and_b32_e32 v4, 0x64, v4
	s_waitcnt lgkmcnt(4)
	v_cvt_pk_bf16_f32 v49, v54, v56
	s_waitcnt lgkmcnt(2)
	v_cvt_pk_bf16_f32 v50, v58, v60
	s_waitcnt lgkmcnt(0)
	v_cvt_pk_bf16_f32 v51, v62, v64
	v_or3_b32 v4, v4, v34, v3
	global_store_dwordx4 v[68:69], v[48:51], off
	v_lshlrev_b32_e32 v4, 10, v4
	s_nop 0
	v_cvt_pk_bf16_f32 v48, v53, v35
	v_cvt_pk_bf16_f32 v49, v55, v57
	v_cvt_pk_bf16_f32 v50, v59, v61
	v_cvt_pk_bf16_f32 v51, v63, v65
	v_lshl_add_u64 v[34:35], v[66:67], 0, v[4:5]
	ds_read2_b32 v[52:53], v40 offset0:49 offset1:57
	ds_read2_b32 v[54:55], v40 offset0:16 offset1:24
	ds_read2_b32 v[56:57], v40 offset0:82 offset1:90
	ds_read2_b32 v[58:59], v40 offset0:115 offset1:123
	ds_read2_b32 v[60:61], v40 offset0:148 offset1:156
	ds_read2_b32 v[62:63], v40 offset0:181 offset1:189
	ds_read2_b32 v[64:65], v40 offset0:214 offset1:222
	ds_read2_b32 v[68:69], v40 offset0:247 offset1:255
	v_or_b32_e32 v4, s12, v42
	global_store_dwordx4 v[34:35], v[48:51], off
	v_lshlrev_b32_e32 v34, 2, v4
	v_lshrrev_b32_e32 v4, 1, v4
	v_and_b32_e32 v34, 0x90, v34
	v_and_b32_e32 v4, 0x68, v4
	v_or3_b32 v4, v4, v34, v3
	v_lshlrev_b32_e32 v4, 10, v4
	s_waitcnt lgkmcnt(6)
	v_cvt_pk_bf16_f32 v48, v54, v52
	s_waitcnt lgkmcnt(4)
	v_cvt_pk_bf16_f32 v49, v56, v58
	s_waitcnt lgkmcnt(2)
	v_cvt_pk_bf16_f32 v50, v60, v62
	s_waitcnt lgkmcnt(0)
	v_cvt_pk_bf16_f32 v51, v64, v68
	v_lshl_add_u64 v[34:35], v[66:67], 0, v[4:5]
	v_or_b32_e32 v4, s12, v43
	global_store_dwordx4 v[34:35], v[48:51], off
	v_lshlrev_b32_e32 v34, 2, v4
	v_lshrrev_b32_e32 v4, 1, v4
	v_and_b32_e32 v34, 0x90, v34
	v_and_b32_e32 v4, 0x6c, v4
	v_or3_b32 v3, v4, v34, v3
	v_lshlrev_b32_e32 v4, 10, v3
	v_cvt_pk_bf16_f32 v48, v55, v53
	v_cvt_pk_bf16_f32 v49, v57, v59
	v_cvt_pk_bf16_f32 v50, v61, v63
	v_cvt_pk_bf16_f32 v51, v65, v69
	v_lshl_add_u64 v[34:35], v[66:67], 0, v[4:5]
	global_store_dwordx4 v[34:35], v[48:51], off
	s_waitcnt lgkmcnt(0)

.LBB0_47:
	s_lshl_b32 s19, s12, 1
	s_lshl_b32 s20, s4, 1
	v_or_b32_e32 v4, s20, v36
	s_add_i32 s22, s19, 4
	s_add_i32 s23, s20, 4
	v_mov_b32_e32 v51, v5
	s_add_i32 s27, s20, 8
	v_lshlrev_b64 v[64:65], 12, v[4:5]
	v_or_b32_e32 v50, s22, v3
	v_or_b32_e32 v4, s23, v36
	v_mov_b32_e32 v49, v5
	v_or_b32_e32 v48, s19, v3
	s_add_i32 s29, s20, 12
	v_lshlrev_b64 v[50:51], 12, v[50:51]
	v_lshlrev_b64 v[66:67], 12, v[4:5]
	v_or_b32_e32 v4, s27, v36
	s_add_i32 s26, s19, 8
	s_add_i32 s28, s19, 12
	s_add_i32 s31, s20, 16
	v_lshlrev_b64 v[48:49], 12, v[48:49]
	v_lshl_add_u64 v[64:65], v[34:35], 0, v[64:65]
	v_lshl_add_u64 v[50:51], v[34:35], 0, v[50:51]
	v_lshlrev_b64 v[68:69], 12, v[4:5]
	v_or_b32_e32 v4, s29, v36
	v_mov_b32_e32 v53, v5
	v_mov_b32_e32 v55, v5
	s_add_i32 s35, s20, 20
	v_or_b32_e32 v52, s26, v3
	v_or_b32_e32 v54, s28, v3
	v_lshl_add_u64 v[48:49], v[34:35], 0, v[48:49]
	v_lshl_add_u64 v[66:67], v[34:35], 0, v[66:67]
	global_load_dword v47, v[64:65], off
	global_load_dword v80, v[48:49], off
	global_load_dword v81, v[66:67], off
	global_load_dword v82, v[50:51], off
	v_lshlrev_b64 v[50:51], 12, v[4:5]
	v_or_b32_e32 v4, s31, v36
	s_add_i32 s30, s19, 16
	s_add_i32 s34, s19, 20
	s_add_i32 s37, s20, 24
	v_lshlrev_b64 v[52:53], 12, v[52:53]
	v_lshlrev_b64 v[54:55], 12, v[54:55]
	v_lshl_add_u64 v[48:49], v[34:35], 0, v[68:69]
	v_lshl_add_u64 v[50:51], v[34:35], 0, v[50:51]
	v_lshlrev_b64 v[64:65], 12, v[4:5]
	v_or_b32_e32 v4, s35, v36
	v_mov_b32_e32 v57, v5
	v_mov_b32_e32 v59, v5
	s_add_i32 s36, s19, 24
	s_add_i32 s38, s19, 28
	s_add_i32 s39, s20, 28
	v_or_b32_e32 v56, s30, v3
	v_or_b32_e32 v58, s34, v3
	v_lshl_add_u64 v[52:53], v[34:35], 0, v[52:53]
	v_lshl_add_u64 v[54:55], v[34:35], 0, v[54:55]
	global_load_dword v83, v[48:49], off
	global_load_dword v84, v[52:53], off
	global_load_dword v85, v[50:51], off
	global_load_dword v86, v[54:55], off
	v_lshlrev_b64 v[50:51], 12, v[4:5]
	v_or_b32_e32 v4, s37, v36
	v_mov_b32_e32 v61, v5
	v_mov_b32_e32 v63, v5
	v_or_b32_e32 v60, s36, v3
	v_or_b32_e32 v62, s38, v3
	v_lshlrev_b64 v[56:57], 12, v[56:57]
	v_lshlrev_b64 v[58:59], 12, v[58:59]
	v_lshl_add_u64 v[48:49], v[34:35], 0, v[64:65]
	v_lshl_add_u64 v[50:51], v[34:35], 0, v[50:51]
	v_lshlrev_b64 v[52:53], 12, v[4:5]
	v_or_b32_e32 v4, s39, v36
	v_lshlrev_b64 v[60:61], 12, v[60:61]
	v_lshlrev_b64 v[62:63], 12, v[62:63]
	v_lshl_add_u64 v[56:57], v[34:35], 0, v[56:57]
	v_lshl_add_u64 v[58:59], v[34:35], 0, v[58:59]
	global_load_dword v87, v[48:49], off
	global_load_dword v88, v[56:57], off
	global_load_dword v89, v[50:51], off
	global_load_dword v90, v[58:59], off
	v_lshl_add_u64 v[48:49], v[34:35], 0, v[52:53]
	v_lshlrev_b64 v[50:51], 12, v[4:5]
	v_lshl_add_u64 v[60:61], v[34:35], 0, v[60:61]
	v_lshl_add_u64 v[62:63], v[34:35], 0, v[62:63]
	v_lshl_add_u64 v[50:51], v[34:35], 0, v[50:51]
	global_load_dword v4, v[48:49], off
	global_load_dword v91, v[60:61], off
	global_load_dword v92, v[50:51], off
	global_load_dword v93, v[62:63], off
	v_or_b32_e32 v50, s19, v1
	v_or_b32_e32 v48, s20, v2
	s_add_i32 s4, s4, 16
	s_add_i32 s12, s12, 16
	s_add_i32 s13, s13, -16
	v_mad_u64_u32 v[48:49], s[20:21], v48, s14, v[8:9]
	v_mad_u64_u32 v[50:51], s[20:21], v50, s14, v[8:9]
	v_or_b32_e32 v49, s22, v1
	v_or_b32_e32 v51, s23, v2
	v_or_b32_e32 v58, s26, v1
	v_or_b32_e32 v56, s27, v2
	v_or_b32_e32 v62, s28, v1
	v_or_b32_e32 v60, s29, v2
	v_or_b32_e32 v66, s30, v1
	v_or_b32_e32 v64, s31, v2
	v_or_b32_e32 v70, s34, v1
	v_or_b32_e32 v68, s35, v2
	v_or_b32_e32 v74, s36, v1
	v_or_b32_e32 v72, s37, v2
	v_or_b32_e32 v78, s38, v1
	v_or_b32_e32 v76, s39, v2
	s_cmp_lg_u32 s13, 0
	v_mad_u64_u32 v[52:53], s[20:21], v51, s14, v[8:9]
	v_mad_u64_u32 v[54:55], s[20:21], v49, s14, v[8:9]
	v_mad_u64_u32 v[56:57], s[20:21], v56, s14, v[8:9]
	v_mad_u64_u32 v[58:59], s[20:21], v58, s14, v[8:9]
	v_mad_u64_u32 v[60:61], s[20:21], v60, s14, v[8:9]
	v_mad_u64_u32 v[62:63], s[20:21], v62, s14, v[8:9]
	v_mad_u64_u32 v[64:65], s[20:21], v64, s14, v[8:9]
	v_mad_u64_u32 v[66:67], s[20:21], v66, s14, v[8:9]
	v_mad_u64_u32 v[68:69], s[20:21], v68, s14, v[8:9]
	v_mad_u64_u32 v[70:71], s[20:21], v70, s14, v[8:9]
	v_mad_u64_u32 v[72:73], s[20:21], v72, s14, v[8:9]
	v_mad_u64_u32 v[74:75], s[20:21], v74, s14, v[8:9]
	v_mad_u64_u32 v[76:77], s[20:21], v76, s14, v[8:9]
	v_mad_u64_u32 v[78:79], s[20:21], v78, s14, v[8:9]
	v_mov_b32_e32 v125, v5
	s_lshl_b32 s19, s12, 1
	s_lshl_b32 s20, s4, 1
	v_or_b32_e32 v124, s20, v36
	s_add_i32 s22, s19, 4
	s_add_i32 s23, s20, 4
	v_mov_b32_e32 v131, v125
	s_add_i32 s27, s20, 8
	v_lshlrev_b64 v[144:145], 12, v[124:125]
	v_or_b32_e32 v130, s22, v3
	v_or_b32_e32 v124, s23, v36
	v_mov_b32_e32 v129, v125
	v_or_b32_e32 v128, s19, v3
	s_add_i32 s29, s20, 12
	v_lshlrev_b64 v[130:131], 12, v[130:131]
	v_lshlrev_b64 v[146:147], 12, v[124:125]
	v_or_b32_e32 v124, s27, v36
	s_add_i32 s26, s19, 8
	s_add_i32 s28, s19, 12
	s_add_i32 s31, s20, 16
	v_lshlrev_b64 v[128:129], 12, v[128:129]
	v_lshl_add_u64 v[144:145], v[34:35], 0, v[144:145]
	v_lshl_add_u64 v[130:131], v[34:35], 0, v[130:131]
	v_lshlrev_b64 v[148:149], 12, v[124:125]
	v_or_b32_e32 v124, s29, v36
	v_mov_b32_e32 v133, v125
	v_mov_b32_e32 v135, v125
	s_add_i32 s35, s20, 20
	v_or_b32_e32 v132, s26, v3
	v_or_b32_e32 v134, s28, v3
	v_lshl_add_u64 v[128:129], v[34:35], 0, v[128:129]
	v_lshl_add_u64 v[146:147], v[34:35], 0, v[146:147]
	global_load_dword v127, v[144:145], off
	global_load_dword v160, v[128:129], off
	global_load_dword v161, v[146:147], off
	global_load_dword v178, v[130:131], off
	v_lshlrev_b64 v[130:131], 12, v[124:125]
	v_or_b32_e32 v124, s31, v36
	s_add_i32 s30, s19, 16
	s_add_i32 s34, s19, 20
	s_add_i32 s37, s20, 24
	v_lshlrev_b64 v[132:133], 12, v[132:133]
	v_lshlrev_b64 v[134:135], 12, v[134:135]
	v_lshl_add_u64 v[128:129], v[34:35], 0, v[148:149]
	v_lshl_add_u64 v[130:131], v[34:35], 0, v[130:131]
	v_lshlrev_b64 v[144:145], 12, v[124:125]
	v_or_b32_e32 v124, s35, v36
	v_mov_b32_e32 v137, v125
	v_mov_b32_e32 v139, v125
	s_add_i32 s36, s19, 24
	s_add_i32 s38, s19, 28
	s_add_i32 s39, s20, 28
	v_or_b32_e32 v136, s30, v3
	v_or_b32_e32 v138, s34, v3
	v_lshl_add_u64 v[132:133], v[34:35], 0, v[132:133]
	v_lshl_add_u64 v[134:135], v[34:35], 0, v[134:135]
	global_load_dword v179, v[128:129], off
	global_load_dword v180, v[132:133], off
	global_load_dword v181, v[130:131], off
	global_load_dword v182, v[134:135], off
	v_lshlrev_b64 v[130:131], 12, v[124:125]
	v_or_b32_e32 v124, s37, v36
	v_mov_b32_e32 v141, v125
	v_mov_b32_e32 v143, v125
	v_or_b32_e32 v140, s36, v3
	v_or_b32_e32 v142, s38, v3
	v_lshlrev_b64 v[136:137], 12, v[136:137]
	v_lshlrev_b64 v[138:139], 12, v[138:139]
	v_lshl_add_u64 v[128:129], v[34:35], 0, v[144:145]
	v_lshl_add_u64 v[130:131], v[34:35], 0, v[130:131]
	v_lshlrev_b64 v[132:133], 12, v[124:125]
	v_or_b32_e32 v124, s39, v36
	v_lshlrev_b64 v[140:141], 12, v[140:141]
	v_lshlrev_b64 v[142:143], 12, v[142:143]
	v_lshl_add_u64 v[136:137], v[34:35], 0, v[136:137]
	v_lshl_add_u64 v[138:139], v[34:35], 0, v[138:139]
	global_load_dword v183, v[128:129], off
	global_load_dword v184, v[136:137], off
	global_load_dword v185, v[130:131], off
	global_load_dword v186, v[138:139], off
	v_lshl_add_u64 v[128:129], v[34:35], 0, v[132:133]
	v_lshlrev_b64 v[130:131], 12, v[124:125]
	v_lshl_add_u64 v[140:141], v[34:35], 0, v[140:141]
	v_lshl_add_u64 v[142:143], v[34:35], 0, v[142:143]
	v_lshl_add_u64 v[130:131], v[34:35], 0, v[130:131]
	global_load_dword v124, v[128:129], off
	global_load_dword v187, v[140:141], off
	global_load_dword v188, v[130:131], off
	global_load_dword v189, v[142:143], off
	v_or_b32_e32 v130, s19, v1
	v_or_b32_e32 v128, s20, v2
	s_add_i32 s4, s4, 16
	s_add_i32 s12, s12, 16
	s_add_i32 s13, s13, -16
	v_mad_u64_u32 v[128:129], s[20:21], v128, s14, v[8:9]
	v_mad_u64_u32 v[130:131], s[20:21], v130, s14, v[8:9]
	v_or_b32_e32 v129, s22, v1
	v_or_b32_e32 v131, s23, v2
	v_or_b32_e32 v138, s26, v1
	v_or_b32_e32 v136, s27, v2
	v_or_b32_e32 v142, s28, v1
	v_or_b32_e32 v140, s29, v2
	v_or_b32_e32 v146, s30, v1
	v_or_b32_e32 v144, s31, v2
	v_or_b32_e32 v150, s34, v1
	v_or_b32_e32 v148, s35, v2
	v_or_b32_e32 v154, s36, v1
	v_or_b32_e32 v152, s37, v2
	v_or_b32_e32 v158, s38, v1
	v_or_b32_e32 v156, s39, v2
	s_cmp_lg_u32 s13, 0
	v_mad_u64_u32 v[132:133], s[20:21], v131, s14, v[8:9]
	v_mad_u64_u32 v[134:135], s[20:21], v129, s14, v[8:9]
	v_mad_u64_u32 v[136:137], s[20:21], v136, s14, v[8:9]
	v_mad_u64_u32 v[138:139], s[20:21], v138, s14, v[8:9]
	v_mad_u64_u32 v[140:141], s[20:21], v140, s14, v[8:9]
	v_mad_u64_u32 v[142:143], s[20:21], v142, s14, v[8:9]
	v_mad_u64_u32 v[144:145], s[20:21], v144, s14, v[8:9]
	v_mad_u64_u32 v[146:147], s[20:21], v146, s14, v[8:9]
	v_mad_u64_u32 v[148:149], s[20:21], v148, s14, v[8:9]
	v_mad_u64_u32 v[150:151], s[20:21], v150, s14, v[8:9]
	v_mad_u64_u32 v[152:153], s[20:21], v152, s14, v[8:9]
	v_mad_u64_u32 v[154:155], s[20:21], v154, s14, v[8:9]
	v_mad_u64_u32 v[156:157], s[20:21], v156, s14, v[8:9]
	v_mad_u64_u32 v[158:159], s[20:21], v158, s14, v[8:9]
	s_waitcnt vmcnt(31)
	ds_write_b32 v48, v47
	s_waitcnt vmcnt(30)
	ds_write_b32 v50, v80
	s_waitcnt vmcnt(29)
	ds_write_b32 v52, v81
	s_waitcnt vmcnt(28)
	ds_write_b32 v54, v82
	s_waitcnt vmcnt(27)
	ds_write_b32 v56, v83
	s_waitcnt vmcnt(26)
	ds_write_b32 v58, v84
	s_waitcnt vmcnt(25)
	ds_write_b32 v60, v85
	s_waitcnt vmcnt(24)
	ds_write_b32 v62, v86
	s_waitcnt vmcnt(23)
	ds_write_b32 v64, v87
	s_waitcnt vmcnt(22)
	ds_write_b32 v66, v88
	s_waitcnt vmcnt(21)
	ds_write_b32 v68, v89
	s_waitcnt vmcnt(20)
	ds_write_b32 v70, v90
	s_waitcnt vmcnt(19)
	ds_write_b32 v72, v4
	s_waitcnt vmcnt(18)
	ds_write_b32 v74, v91
	s_waitcnt vmcnt(17)
	ds_write_b32 v76, v92
	s_waitcnt vmcnt(16)
	ds_write_b32 v78, v93
	s_waitcnt vmcnt(15)
	ds_write_b32 v128, v127
	s_waitcnt vmcnt(14)
	ds_write_b32 v130, v160
	s_waitcnt vmcnt(13)
	ds_write_b32 v132, v161
	s_waitcnt vmcnt(12)
	ds_write_b32 v134, v178
	s_waitcnt vmcnt(11)
	ds_write_b32 v136, v179
	s_waitcnt vmcnt(10)
	ds_write_b32 v138, v180
	s_waitcnt vmcnt(9)
	ds_write_b32 v140, v181
	s_waitcnt vmcnt(8)
	ds_write_b32 v142, v182
	s_waitcnt vmcnt(7)
	ds_write_b32 v144, v183
	s_waitcnt vmcnt(6)
	ds_write_b32 v146, v184
	s_waitcnt vmcnt(5)
	ds_write_b32 v148, v185
	s_waitcnt vmcnt(4)
	ds_write_b32 v150, v186
	s_waitcnt vmcnt(3)
	ds_write_b32 v152, v124
	s_waitcnt vmcnt(2)
	ds_write_b32 v154, v187
	s_waitcnt vmcnt(1)
	ds_write_b32 v156, v188
	s_waitcnt vmcnt(0)
	ds_write_b32 v158, v189
	v_or_b32_e32 v4, s2, v37
	s_and_b32 s4, s2, 0x300
	s_and_b32 s12, s2, 0xe0
	v_lshlrev_b32_e32 v4, 2, v4
	s_lshl_b32 s2, s18, 4
	s_waitcnt lgkmcnt(0)
	v_or_b32_e32 v3, s4, v38
	v_and_b32_e32 v4, 0x90, v4
	s_and_b32 s2, s2, 0x60
	s_lshl_b32 s4, s3, 1
	ds_read2_b32 v[34:35], v40 offset0:33 offset1:41
	ds_read2_b32 v[52:53], v40 offset1:8
	ds_read2_b32 v[54:55], v40 offset0:66 offset1:74
	ds_read2_b32 v[56:57], v40 offset0:99 offset1:107
	ds_read2_b32 v[58:59], v40 offset0:132 offset1:140
	ds_read2_b32 v[60:61], v40 offset0:165 offset1:173
	ds_read2_b32 v[62:63], v40 offset0:198 offset1:206
	ds_read2_b32 v[64:65], v40 offset0:231 offset1:239
	v_or3_b32 v4, s2, v4, v3
	v_lshl_add_u64 v[66:67], v[32:33], 0, s[4:5]
	v_lshlrev_b32_e32 v4, 11, v4
	v_lshl_add_u64 v[68:69], v[66:67], 0, v[4:5]
	v_or_b32_e32 v4, s12, v41
	s_waitcnt lgkmcnt(6)
	v_cvt_pk_bf16_f32 v48, v52, v34
	v_lshlrev_b32_e32 v34, 2, v4
	v_lshrrev_b32_e32 v4, 1, v4
	v_and_b32_e32 v34, 0x90, v34
	v_and_b32_e32 v4, 0x64, v4
	s_waitcnt lgkmcnt(4)
	v_cvt_pk_bf16_f32 v49, v54, v56
	s_waitcnt lgkmcnt(2)
	v_cvt_pk_bf16_f32 v50, v58, v60
	s_waitcnt lgkmcnt(0)
	v_cvt_pk_bf16_f32 v51, v62, v64
	v_or3_b32 v4, v4, v34, v3
	global_store_dwordx4 v[68:69], v[48:51], off
	v_lshlrev_b32_e32 v4, 11, v4
	s_nop 0
	v_cvt_pk_bf16_f32 v48, v53, v35
	v_cvt_pk_bf16_f32 v49, v55, v57
	v_cvt_pk_bf16_f32 v50, v59, v61
	v_cvt_pk_bf16_f32 v51, v63, v65
	v_lshl_add_u64 v[34:35], v[66:67], 0, v[4:5]
	ds_read2_b32 v[52:53], v40 offset0:49 offset1:57
	ds_read2_b32 v[54:55], v40 offset0:16 offset1:24
	ds_read2_b32 v[56:57], v40 offset0:82 offset1:90
	ds_read2_b32 v[58:59], v40 offset0:115 offset1:123
	ds_read2_b32 v[60:61], v40 offset0:148 offset1:156
	ds_read2_b32 v[62:63], v40 offset0:181 offset1:189
	ds_read2_b32 v[64:65], v40 offset0:214 offset1:222
	ds_read2_b32 v[68:69], v40 offset0:247 offset1:255
	v_or_b32_e32 v4, s12, v42
	global_store_dwordx4 v[34:35], v[48:51], off
	v_lshlrev_b32_e32 v34, 2, v4
	v_lshrrev_b32_e32 v4, 1, v4
	v_and_b32_e32 v34, 0x90, v34
	v_and_b32_e32 v4, 0x68, v4
	v_or3_b32 v4, v4, v34, v3
	v_lshlrev_b32_e32 v4, 11, v4
	s_waitcnt lgkmcnt(6)
	v_cvt_pk_bf16_f32 v48, v54, v52
	s_waitcnt lgkmcnt(4)
	v_cvt_pk_bf16_f32 v49, v56, v58
	s_waitcnt lgkmcnt(2)
	v_cvt_pk_bf16_f32 v50, v60, v62
	s_waitcnt lgkmcnt(0)
	v_cvt_pk_bf16_f32 v51, v64, v68
	v_lshl_add_u64 v[34:35], v[66:67], 0, v[4:5]
	v_or_b32_e32 v4, s12, v43
	global_store_dwordx4 v[34:35], v[48:51], off
	v_lshlrev_b32_e32 v34, 2, v4
	v_lshrrev_b32_e32 v4, 1, v4
	v_and_b32_e32 v34, 0x90, v34
	v_and_b32_e32 v4, 0x6c, v4
	v_or3_b32 v3, v4, v34, v3
	v_lshlrev_b32_e32 v4, 11, v3
	v_cvt_pk_bf16_f32 v48, v55, v53
	v_cvt_pk_bf16_f32 v49, v57, v59
	v_cvt_pk_bf16_f32 v50, v61, v63
	v_cvt_pk_bf16_f32 v51, v65, v69
	v_lshl_add_u64 v[34:35], v[66:67], 0, v[4:5]
	global_store_dwordx4 v[34:35], v[48:51], off
	s_waitcnt lgkmcnt(0)

.LBB0_51:
	s_lshl_b32 s19, s3, 1
	s_lshl_b32 s22, s4, 1
	v_or_b32_e32 v36, s19, v3
	v_or_b32_e32 v47, s22, v4
	s_add_i32 s23, s19, 4
	s_add_i32 s26, s22, 4
	s_add_i32 s27, s19, 8
	s_add_i32 s28, s22, 8
	s_add_i32 s29, s19, 12
	s_add_i32 s30, s22, 12
	s_add_i32 s31, s19, 16
	s_add_i32 s34, s22, 16
	s_add_i32 s35, s19, 20
	s_add_i32 s36, s22, 20
	s_add_i32 s37, s19, 24
	s_add_i32 s38, s22, 24
	s_add_i32 s39, s19, 28
	s_add_i32 s40, s22, 28
	v_mad_i64_i32 v[48:49], s[20:21], v47, s17, v[34:35]
	v_mad_i64_i32 v[50:51], s[20:21], v36, s17, v[34:35]
	v_or_b32_e32 v36, s23, v3
	v_or_b32_e32 v47, s26, v4
	v_or_b32_e32 v58, s27, v3
	v_or_b32_e32 v56, s28, v4
	v_or_b32_e32 v62, s29, v3
	v_or_b32_e32 v60, s30, v4
	v_or_b32_e32 v66, s31, v3
	v_or_b32_e32 v64, s34, v4
	v_or_b32_e32 v70, s35, v3
	v_or_b32_e32 v68, s36, v4
	v_or_b32_e32 v74, s37, v3
	v_or_b32_e32 v72, s38, v4
	v_or_b32_e32 v78, s39, v3
	v_or_b32_e32 v76, s40, v4
	v_mad_i64_i32 v[52:53], s[20:21], v47, s17, v[34:35]
	v_mad_i64_i32 v[54:55], s[20:21], v36, s17, v[34:35]
	v_mad_i64_i32 v[56:57], s[20:21], v56, s17, v[34:35]
	v_mad_i64_i32 v[58:59], s[20:21], v58, s17, v[34:35]
	v_mad_i64_i32 v[60:61], s[20:21], v60, s17, v[34:35]
	v_mad_i64_i32 v[62:63], s[20:21], v62, s17, v[34:35]
	v_mad_i64_i32 v[64:65], s[20:21], v64, s17, v[34:35]
	v_mad_i64_i32 v[66:67], s[20:21], v66, s17, v[34:35]
	v_mad_i64_i32 v[68:69], s[20:21], v68, s17, v[34:35]
	v_mad_i64_i32 v[70:71], s[20:21], v70, s17, v[34:35]
	v_mad_i64_i32 v[72:73], s[20:21], v72, s17, v[34:35]
	v_mad_i64_i32 v[74:75], s[20:21], v74, s17, v[34:35]
	v_mad_i64_i32 v[76:77], s[20:21], v76, s17, v[34:35]
	v_mad_i64_i32 v[78:79], s[20:21], v78, s17, v[34:35]
	global_load_dword v36, v[48:49], off
	global_load_dword v47, v[50:51], off
	global_load_dword v80, v[52:53], off
	global_load_dword v81, v[54:55], off
	global_load_dword v82, v[56:57], off
	global_load_dword v83, v[58:59], off
	global_load_dword v84, v[60:61], off
	global_load_dword v85, v[62:63], off
	global_load_dword v86, v[64:65], off
	global_load_dword v87, v[66:67], off
	global_load_dword v88, v[68:69], off
	global_load_dword v89, v[70:71], off
	global_load_dword v90, v[72:73], off
	global_load_dword v91, v[74:75], off
	global_load_dword v92, v[76:77], off
	global_load_dword v93, v[78:79], off
	v_or_b32_e32 v50, s19, v1
	v_or_b32_e32 v48, s22, v2
	s_add_i32 s4, s4, 16
	s_add_i32 s3, s3, 16
	s_add_i32 s13, s13, -16
	v_mad_u64_u32 v[48:49], s[20:21], v48, s14, v[8:9]
	v_mad_u64_u32 v[50:51], s[20:21], v50, s14, v[8:9]
	v_or_b32_e32 v49, s23, v1
	v_or_b32_e32 v51, s26, v2
	v_or_b32_e32 v58, s27, v1
	v_or_b32_e32 v56, s28, v2
	v_or_b32_e32 v62, s29, v1
	v_or_b32_e32 v60, s30, v2
	v_or_b32_e32 v66, s31, v1
	v_or_b32_e32 v64, s34, v2
	v_or_b32_e32 v70, s35, v1
	v_or_b32_e32 v68, s36, v2
	v_or_b32_e32 v74, s37, v1
	v_or_b32_e32 v72, s38, v2
	v_or_b32_e32 v78, s39, v1
	v_or_b32_e32 v76, s40, v2
	s_cmp_lg_u32 s13, 0
	v_mad_u64_u32 v[52:53], s[20:21], v51, s14, v[8:9]
	v_mad_u64_u32 v[54:55], s[20:21], v49, s14, v[8:9]
	v_mad_u64_u32 v[56:57], s[20:21], v56, s14, v[8:9]
	v_mad_u64_u32 v[58:59], s[20:21], v58, s14, v[8:9]
	v_mad_u64_u32 v[60:61], s[20:21], v60, s14, v[8:9]
	v_mad_u64_u32 v[62:63], s[20:21], v62, s14, v[8:9]
	v_mad_u64_u32 v[64:65], s[20:21], v64, s14, v[8:9]
	v_mad_u64_u32 v[66:67], s[20:21], v66, s14, v[8:9]
	v_mad_u64_u32 v[68:69], s[20:21], v68, s14, v[8:9]
	v_mad_u64_u32 v[70:71], s[20:21], v70, s14, v[8:9]
	v_mad_u64_u32 v[72:73], s[20:21], v72, s14, v[8:9]
	v_mad_u64_u32 v[74:75], s[20:21], v74, s14, v[8:9]
	v_mad_u64_u32 v[76:77], s[20:21], v76, s14, v[8:9]
	v_mad_u64_u32 v[78:79], s[20:21], v78, s14, v[8:9]
	s_lshl_b32 s19, s3, 1
	s_lshl_b32 s22, s4, 1
	v_or_b32_e32 v124, s19, v3
	v_or_b32_e32 v127, s22, v4
	s_add_i32 s23, s19, 4
	s_add_i32 s26, s22, 4
	s_add_i32 s27, s19, 8
	s_add_i32 s28, s22, 8
	s_add_i32 s29, s19, 12
	s_add_i32 s30, s22, 12
	s_add_i32 s31, s19, 16
	s_add_i32 s34, s22, 16
	s_add_i32 s35, s19, 20
	s_add_i32 s36, s22, 20
	s_add_i32 s37, s19, 24
	s_add_i32 s38, s22, 24
	s_add_i32 s39, s19, 28
	s_add_i32 s40, s22, 28
	v_mad_i64_i32 v[128:129], s[20:21], v127, s17, v[34:35]
	v_mad_i64_i32 v[130:131], s[20:21], v124, s17, v[34:35]
	v_or_b32_e32 v124, s23, v3
	v_or_b32_e32 v127, s26, v4
	v_or_b32_e32 v138, s27, v3
	v_or_b32_e32 v136, s28, v4
	v_or_b32_e32 v142, s29, v3
	v_or_b32_e32 v140, s30, v4
	v_or_b32_e32 v146, s31, v3
	v_or_b32_e32 v144, s34, v4
	v_or_b32_e32 v150, s35, v3
	v_or_b32_e32 v148, s36, v4
	v_or_b32_e32 v154, s37, v3
	v_or_b32_e32 v152, s38, v4
	v_or_b32_e32 v158, s39, v3
	v_or_b32_e32 v156, s40, v4
	v_mad_i64_i32 v[132:133], s[20:21], v127, s17, v[34:35]
	v_mad_i64_i32 v[134:135], s[20:21], v124, s17, v[34:35]
	v_mad_i64_i32 v[136:137], s[20:21], v136, s17, v[34:35]
	v_mad_i64_i32 v[138:139], s[20:21], v138, s17, v[34:35]
	v_mad_i64_i32 v[140:141], s[20:21], v140, s17, v[34:35]
	v_mad_i64_i32 v[142:143], s[20:21], v142, s17, v[34:35]
	v_mad_i64_i32 v[144:145], s[20:21], v144, s17, v[34:35]
	v_mad_i64_i32 v[146:147], s[20:21], v146, s17, v[34:35]
	v_mad_i64_i32 v[148:149], s[20:21], v148, s17, v[34:35]
	v_mad_i64_i32 v[150:151], s[20:21], v150, s17, v[34:35]
	v_mad_i64_i32 v[152:153], s[20:21], v152, s17, v[34:35]
	v_mad_i64_i32 v[154:155], s[20:21], v154, s17, v[34:35]
	v_mad_i64_i32 v[156:157], s[20:21], v156, s17, v[34:35]
	v_mad_i64_i32 v[158:159], s[20:21], v158, s17, v[34:35]
	global_load_dword v124, v[128:129], off
	global_load_dword v127, v[130:131], off
	global_load_dword v160, v[132:133], off
	global_load_dword v161, v[134:135], off
	global_load_dword v178, v[136:137], off
	global_load_dword v179, v[138:139], off
	global_load_dword v180, v[140:141], off
	global_load_dword v181, v[142:143], off
	global_load_dword v182, v[144:145], off
	global_load_dword v183, v[146:147], off
	global_load_dword v184, v[148:149], off
	global_load_dword v185, v[150:151], off
	global_load_dword v186, v[152:153], off
	global_load_dword v187, v[154:155], off
	global_load_dword v188, v[156:157], off
	global_load_dword v189, v[158:159], off
	v_or_b32_e32 v130, s19, v1
	v_or_b32_e32 v128, s22, v2
	s_add_i32 s4, s4, 16
	s_add_i32 s3, s3, 16
	s_add_i32 s13, s13, -16
	v_mad_u64_u32 v[128:129], s[20:21], v128, s14, v[8:9]
	v_mad_u64_u32 v[130:131], s[20:21], v130, s14, v[8:9]
	v_or_b32_e32 v129, s23, v1
	v_or_b32_e32 v131, s26, v2
	v_or_b32_e32 v138, s27, v1
	v_or_b32_e32 v136, s28, v2
	v_or_b32_e32 v142, s29, v1
	v_or_b32_e32 v140, s30, v2
	v_or_b32_e32 v146, s31, v1
	v_or_b32_e32 v144, s34, v2
	v_or_b32_e32 v150, s35, v1
	v_or_b32_e32 v148, s36, v2
	v_or_b32_e32 v154, s37, v1
	v_or_b32_e32 v152, s38, v2
	v_or_b32_e32 v158, s39, v1
	v_or_b32_e32 v156, s40, v2
	s_cmp_lg_u32 s13, 0
	v_mad_u64_u32 v[132:133], s[20:21], v131, s14, v[8:9]
	v_mad_u64_u32 v[134:135], s[20:21], v129, s14, v[8:9]
	v_mad_u64_u32 v[136:137], s[20:21], v136, s14, v[8:9]
	v_mad_u64_u32 v[138:139], s[20:21], v138, s14, v[8:9]
	v_mad_u64_u32 v[140:141], s[20:21], v140, s14, v[8:9]
	v_mad_u64_u32 v[142:143], s[20:21], v142, s14, v[8:9]
	v_mad_u64_u32 v[144:145], s[20:21], v144, s14, v[8:9]
	v_mad_u64_u32 v[146:147], s[20:21], v146, s14, v[8:9]
	v_mad_u64_u32 v[148:149], s[20:21], v148, s14, v[8:9]
	v_mad_u64_u32 v[150:151], s[20:21], v150, s14, v[8:9]
	v_mad_u64_u32 v[152:153], s[20:21], v152, s14, v[8:9]
	v_mad_u64_u32 v[154:155], s[20:21], v154, s14, v[8:9]
	v_mad_u64_u32 v[156:157], s[20:21], v156, s14, v[8:9]
	v_mad_u64_u32 v[158:159], s[20:21], v158, s14, v[8:9]
	s_waitcnt vmcnt(31)
	ds_write_b32 v48, v36
	s_waitcnt vmcnt(30)
	ds_write_b32 v50, v47
	s_waitcnt vmcnt(29)
	ds_write_b32 v52, v80
	s_waitcnt vmcnt(28)
	ds_write_b32 v54, v81
	s_waitcnt vmcnt(27)
	ds_write_b32 v56, v82
	s_waitcnt vmcnt(26)
	ds_write_b32 v58, v83
	s_waitcnt vmcnt(25)
	ds_write_b32 v60, v84
	s_waitcnt vmcnt(24)
	ds_write_b32 v62, v85
	s_waitcnt vmcnt(23)
	ds_write_b32 v64, v86
	s_waitcnt vmcnt(22)
	ds_write_b32 v66, v87
	s_waitcnt vmcnt(21)
	ds_write_b32 v68, v88
	s_waitcnt vmcnt(20)
	ds_write_b32 v70, v89
	s_waitcnt vmcnt(19)
	ds_write_b32 v72, v90
	s_waitcnt vmcnt(18)
	ds_write_b32 v74, v91
	s_waitcnt vmcnt(17)
	ds_write_b32 v76, v92
	s_waitcnt vmcnt(16)
	ds_write_b32 v78, v93
	s_waitcnt vmcnt(15)
	ds_write_b32 v128, v124
	s_waitcnt vmcnt(14)
	ds_write_b32 v130, v127
	s_waitcnt vmcnt(13)
	ds_write_b32 v132, v160
	s_waitcnt vmcnt(12)
	ds_write_b32 v134, v161
	s_waitcnt vmcnt(11)
	ds_write_b32 v136, v178
	s_waitcnt vmcnt(10)
	ds_write_b32 v138, v179
	s_waitcnt vmcnt(9)
	ds_write_b32 v140, v180
	s_waitcnt vmcnt(8)
	ds_write_b32 v142, v181
	s_waitcnt vmcnt(7)
	ds_write_b32 v144, v182
	s_waitcnt vmcnt(6)
	ds_write_b32 v146, v183
	s_waitcnt vmcnt(5)
	ds_write_b32 v148, v184
	s_waitcnt vmcnt(4)
	ds_write_b32 v150, v185
	s_waitcnt vmcnt(3)
	ds_write_b32 v152, v186
	s_waitcnt vmcnt(2)
	ds_write_b32 v154, v187
	s_waitcnt vmcnt(1)
	ds_write_b32 v156, v188
	s_waitcnt vmcnt(0)
	ds_write_b32 v158, v189
	s_and_b32 s4, s2, 0xe0
	s_waitcnt lgkmcnt(0)
	v_or_b32_e32 v4, s4, v37
	s_and_b32 s3, s2, 0xffffff00
	ds_read2_b32 v[34:35], v40 offset0:33 offset1:41
	ds_read2_b32 v[52:53], v40 offset1:8
	ds_read2_b32 v[54:55], v40 offset0:66 offset1:74
	ds_read2_b32 v[56:57], v40 offset0:99 offset1:107
	ds_read2_b32 v[58:59], v40 offset0:132 offset1:140
	ds_read2_b32 v[60:61], v40 offset0:165 offset1:173
	ds_read2_b32 v[62:63], v40 offset0:198 offset1:206
	ds_read2_b32 v[64:65], v40 offset0:231 offset1:239
	v_lshlrev_b32_e32 v4, 2, v4
	s_lshr_b32 s2, s2, 1
	v_or_b32_e32 v3, s3, v38
	v_and_b32_e32 v4, 0x90, v4
	s_and_b32 s2, s2, 0x60
	v_or3_b32 v68, s2, v4, v3
	v_or_b32_e32 v4, s4, v41
	s_ashr_i32 s13, s12, 31
	s_waitcnt lgkmcnt(6)
	v_cvt_pk_bf16_f32 v48, v52, v34
	v_ashrrev_i32_e32 v69, 31, v68
	v_lshlrev_b32_e32 v34, 2, v4
	v_lshrrev_b32_e32 v4, 1, v4
	v_lshl_add_u64 v[66:67], s[12:13], 1, v[22:23]
	v_lshlrev_b64 v[68:69], 11, v[68:69]
	v_and_b32_e32 v34, 0x90, v34
	v_and_b32_e32 v4, 0x64, v4
	s_waitcnt lgkmcnt(4)
	v_cvt_pk_bf16_f32 v49, v54, v56
	s_waitcnt lgkmcnt(2)
	v_cvt_pk_bf16_f32 v50, v58, v60
	s_waitcnt lgkmcnt(0)
	v_cvt_pk_bf16_f32 v51, v62, v64
	v_lshl_add_u64 v[68:69], v[66:67], 0, v[68:69]
	v_or3_b32 v34, v34, v4, v3
	global_store_dwordx4 v[68:69], v[48:51], off
	v_or_b32_e32 v4, s4, v42
	s_nop 0
	v_cvt_pk_bf16_f32 v48, v53, v35
	v_ashrrev_i32_e32 v35, 31, v34
	v_lshlrev_b64 v[34:35], 11, v[34:35]
	v_cvt_pk_bf16_f32 v49, v55, v57
	v_cvt_pk_bf16_f32 v50, v59, v61
	v_cvt_pk_bf16_f32 v51, v63, v65
	v_lshl_add_u64 v[34:35], v[66:67], 0, v[34:35]
	ds_read2_b32 v[52:53], v40 offset0:49 offset1:57
	ds_read2_b32 v[54:55], v40 offset0:16 offset1:24
	ds_read2_b32 v[56:57], v40 offset0:82 offset1:90
	ds_read2_b32 v[58:59], v40 offset0:115 offset1:123
	ds_read2_b32 v[60:61], v40 offset0:148 offset1:156
	ds_read2_b32 v[62:63], v40 offset0:181 offset1:189
	ds_read2_b32 v[64:65], v40 offset0:214 offset1:222
	ds_read2_b32 v[68:69], v40 offset0:247 offset1:255
	global_store_dwordx4 v[34:35], v[48:51], off
	v_lshlrev_b32_e32 v34, 2, v4
	v_lshrrev_b32_e32 v4, 1, v4
	v_and_b32_e32 v34, 0x90, v34
	v_and_b32_e32 v4, 0x68, v4
	v_or3_b32 v34, v34, v4, v3
	v_ashrrev_i32_e32 v35, 31, v34
	v_lshlrev_b64 v[34:35], 11, v[34:35]
	s_waitcnt lgkmcnt(6)
	v_cvt_pk_bf16_f32 v48, v54, v52
	s_waitcnt lgkmcnt(4)
	v_cvt_pk_bf16_f32 v49, v56, v58
	s_waitcnt lgkmcnt(2)
	v_cvt_pk_bf16_f32 v50, v60, v62
	s_waitcnt lgkmcnt(0)
	v_cvt_pk_bf16_f32 v51, v64, v68
	v_lshl_add_u64 v[34:35], v[66:67], 0, v[34:35]
	v_or_b32_e32 v4, s4, v43
	global_store_dwordx4 v[34:35], v[48:51], off
	v_lshlrev_b32_e32 v34, 2, v4
	v_lshrrev_b32_e32 v4, 1, v4
	v_and_b32_e32 v34, 0x90, v34
	v_and_b32_e32 v4, 0x6c, v4
	v_or3_b32 v34, v34, v4, v3
	v_ashrrev_i32_e32 v35, 31, v34
	v_lshlrev_b64 v[34:35], 11, v[34:35]
	v_cvt_pk_bf16_f32 v48, v55, v53
	v_cvt_pk_bf16_f32 v49, v57, v59
	v_cvt_pk_bf16_f32 v50, v61, v63
	v_cvt_pk_bf16_f32 v51, v65, v69
	v_lshl_add_u64 v[34:35], v[66:67], 0, v[34:35]
	global_store_dwordx4 v[34:35], v[48:51], off
	s_waitcnt lgkmcnt(0)
	s_branch .LBB0_8

.LBB0_84:
	s_cmp_lt_i32 s82, 2
	s_cselect_b64 s[0:1], -1, 0
	s_and_b64 s[0:1], s[0:1], s[2:3]
	s_andn2_b64 vcc, exec, s[0:1]
	s_cbranch_vccnz .LBB0_105
	s_mov_b64 s[2:3], 0
	v_readlane_b32 s26, v254, 0
	v_mov_b32_e32 v0, v230
	v_mov_b32_e32 v8, v230
	s_cmpk_gt_i32 s26, 0x7f
	v_readfirstlane_b32 s27, v8
	s_cbranch_scc1 .LBB0_105
	s_ashr_i32 s28, s26, 31
	s_lshr_b32 s4, s28, 29
	s_add_i32 s8, s26, s4
	s_and_b32 s4, s8, -8
	s_sub_i32 s6, s26, s4
	s_cmp_gt_i32 s6, -1
	s_cbranch_scc0 .LBB0_88
	s_lshl_b32 s7, s6, 4
	s_ashr_i32 s4, s8, 3
	s_cbranch_execz .LBB0_89
	s_branch .LBB0_90
	s_nop 0
	s_nop 0
	s_nop 0
	s_nop 0
	s_nop 0
	s_nop 0
	s_nop 0
	s_nop 0
	s_nop 0
